# nt policy on read-once residual X loads in out-proj/down-proj epilogues and on the MLA Q fragment loads
# speedup vs baseline: 1.0035x; 1.0035x over previous
; DI int opaque_tid() { int t = threadIdx.x; asm volatile("" : "+v"(t)); return t; }
;     DI const bf16_t* Q() const { return (const bf16_t*)(ws + WS_Q); }
;     DI const bf16_t* KV() const { return (const bf16_t*)(ws + WS_KV); }
;     DI const bf16_t* KPE() const { return (const bf16_t*)(ws + WS_KPE); }
; #define MLA_LOAD() do { sreg[0] = *(const u32x4*)(kp0); sreg[1] = *(const u32x4*)(kp0 + 64); sreg[2] = *(const u32x4*)(kp0 + 128); sreg[3] = *(const u32x4*)(kp0 + 192); \
;         sreg[4] = *(const u32x4*)(kp1); kp0 += (size_t)64 * 2048; kp1 += (size_t)64 * 64; } while (0)
; #define MLA_WRITE(buf) do { LAS unsigned char* kd_ = lds + (buf) * BUFB + lkey * KSTR + lq * 16; LAS unsigned char* vd_ = lds + (buf) * BUFB + 64 * KSTR + lkey * VSTR + lq * 16; \
;         *(LAS u32x4*)(kd_) = sreg[0]; *(LAS u32x4*)(kd_ + 128) = sreg[1]; *(LAS u32x4*)(kd_ + 256) = sreg[4]; *(LAS u32x4*)(vd_) = sreg[2]; *(LAS u32x4*)(vd_ + 128) = sreg[3]; } while (0)
; template <bool ATOM>
; DI void mla_unit(LAS unsigned char* lds, const AttnPtrs& P, int b, int hd, int qb) {
;     ...
;     const int tid = opaque_tid(), lane = tid & 63, wid = __builtin_amdgcn_readfirstlane(tid >> 6), r = lane & 31, h = lane >> 5, rg = wid & 3, kh = wid >> 2;
;     const int fq_ = qb * 128 + rg * 32 + r;
;     const size_t tokq = (size_t)b * 2048 + fq_;
;     bf16x8 qf[NKK];
;     { const bf16_t* qp = P.Q() + tokq * 1536 + hd * 192;
; #pragma unroll
;       for (int kk = 0; kk < NKK; ++kk) qf[kk] = *(const bf16x8*)(qp + kk * 16 + 8 * h); }
;     f32x16 o[NDV];
; #pragma unroll
;     for (int d = 0; d < NDV; ++d)
; #pragma unroll
;         for (int i = 0; i < 16; ++i) o[d][i] = 0.f;
;     float mrun = -INFINITY, lrun = 0.f;
;     const int lkey = tid >> 3, lq = tid & 7;
;     const bf16_t* kp0 = P.KV() + ((size_t)b * 2048 + lkey) * 2048 + hd * 256 + lq * 8;
;     const bf16_t* kp1 = P.KPE() + ((size_t)b * 2048 + lkey) * 64 + lq * 8;
;     u32x4 sreg[5];
;     ...
;     const int nsteps = 2 * (qb + 1);
;     __syncthreads();
;     MLA_LOAD(); MLA_WRITE(0);
;     MLA_LOAD();
;     __syncthreads();
.LBB0_1048:
	s_and_b64 s[14:15], s[8:9], exec
	v_mov_b32_e32 v30, v188
	s_cselect_b32 s4, s1, s0
	s_and_b32 s16, s4, 7
	v_readfirstlane_b32 s18, v30
	s_bfe_u32 s19, s18, 0x20006
	s_ashr_i32 s14, s4, 6
	s_lshl_b32 s23, s16, 7
	s_lshl_b32 s15, s19, 5
	v_and_b32_e32 v31, 31, v30
	s_or_b32 s34, s15, s23
	s_ashr_i32 s15, s14, 31
	v_or_b32_e32 v214, s34, v31
	s_lshl_b64 s[50:51], s[14:15], 11
	s_bfe_u32 s4, s4, 0x30003
	v_or_b32_e32 v130, s50, v214
	s_waitcnt lgkmcnt(0)
	v_mov_b64_e32 v[0:1], s[10:11]
	v_mad_u64_u32 v[0:1], s[14:15], v130, s90, v[0:1]
	s_mul_i32 s17, s4, 0xc0
	v_bfe_u32 v32, v30, 5, 1
	v_mad_i32_i24 v1, s51, v207, v1
	s_lshl_b32 s38, s17, 1
	v_lshl_add_u64 v[0:1], v[0:1], 0, s[38:39]
	v_lshlrev_b32_e32 v128, 4, v32
	v_ashrrev_i32_e32 v20, 3, v30
	v_lshl_add_u64 v[0:1], v[0:1], 0, v[128:129]
	v_ashrrev_i32_e32 v21, 31, v20
	global_load_dwordx4 v[180:183], v[0:1], off nt
	global_load_dwordx4 v[176:179], v[0:1], off offset:32 nt
	global_load_dwordx4 v[172:175], v[0:1], off offset:64 nt
	global_load_dwordx4 v[168:171], v[0:1], off offset:96 nt
	global_load_dwordx4 v[164:167], v[0:1], off offset:128 nt
	global_load_dwordx4 v[160:163], v[0:1], off offset:160 nt
	global_load_dwordx4 v[156:159], v[0:1], off offset:192 nt
	global_load_dwordx4 v[152:155], v[0:1], off offset:224 nt
	global_load_dwordx4 v[148:151], v[0:1], off offset:256 nt
	global_load_dwordx4 v[144:147], v[0:1], off offset:288 nt
	global_load_dwordx4 v[140:143], v[0:1], off offset:320 nt
	global_load_dwordx4 v[136:139], v[0:1], off offset:352 nt
	v_lshl_add_u64 v[0:1], s[50:51], 0, v[20:21]
	v_lshlrev_b64 v[2:3], 12, v[0:1]
	v_lshlrev_b32_e32 v4, 4, v30
	v_lshlrev_b64 v[0:1], 7, v[0:1]
	v_lshl_add_u64 v[2:3], s[12:13], 0, v[2:3]
	s_lshl_b32 s38, s4, 9
	v_and_b32_e32 v116, 0x70, v4
	v_mov_b32_e32 v117, v129
	v_lshl_add_u64 v[0:1], s[42:43], 0, v[0:1]
	v_lshl_add_u64 v[2:3], v[2:3], 0, s[38:39]
	v_lshl_add_u64 v[24:25], v[0:1], 0, v[116:117]
	v_lshl_add_u64 v[22:23], v[2:3], 0, v[116:117]
	s_barrier
	global_load_dwordx4 v[0:3], v[24:25], off
	global_load_dwordx4 v[4:7], v[22:23], off
	global_load_dwordx4 v[8:11], v[22:23], off offset:128
	global_load_dwordx4 v[12:15], v[22:23], off offset:256
	global_load_dwordx4 v[16:19], v[22:23], off offset:384
	v_add_co_u32_e32 v26, vcc, s89, v22
	s_movk_i32 s14, 0x2000
	s_nop 0
	v_addc_co_u32_e32 v27, vcc, 0, v23, vcc
	global_load_dwordx4 v[96:99], v[26:27], off
	global_load_dwordx4 v[100:103], v[26:27], off offset:128
	global_load_dwordx4 v[104:107], v[26:27], off offset:256
	v_add_co_u32_e32 v28, vcc, s14, v24
	s_lshl_b32 s48, s4, 8
	s_nop 0
	v_addc_co_u32_e32 v29, vcc, 0, v25, vcc
	global_load_dwordx4 v[108:111], v[26:27], off offset:384
	global_load_dwordx4 v[112:115], v[28:29], off
	s_movk_i32 s4, 0x190
	v_mul_lo_u32 v117, v20, s4
	s_ashr_i32 s22, s18, 8
	s_movk_i32 s38, 0x120
	v_add3_u32 v26, 0, v117, v116
	s_movk_i32 s35, 0xff90
	v_mul_lo_u32 v122, v20, s38
	v_mad_u64_u32 v[20:21], s[36:37], v20, s35, v[26:27]
	s_lshl_b32 s35, s22, 5
	v_lshlrev_b32_e32 v209, 2, v32
	s_mov_b64 s[36:37], 0x4000
	v_and_b32_e32 v208, 63, v30
	v_lshl_add_u64 v[118:119], v[24:25], 0, s[36:37]
	s_mov_b64 s[36:37], 0x80000
	v_lshl_add_u64 v[120:121], v[22:23], 0, s[36:37]
	v_mov_b32_e32 v21, v129
	v_mov_b32_e32 v22, v129
	v_mov_b32_e32 v23, v129
	v_mov_b32_e32 v24, v129
	v_mov_b32_e32 v25, v129
	v_mov_b32_e32 v27, v129
	v_mov_b32_e32 v28, v129
	v_mov_b32_e32 v29, v129
	s_mov_b32 s14, 0
	s_lshl_b32 s15, s16, 1
	v_mov_b32_e32 v131, s51
	s_or_b32 s36, s34, 31
	s_or_b32 s37, s23, 64
	v_or_b32_e32 v123, s35, v209
	v_mov_b32_e32 v213, 0
	v_mov_b32_e32 v124, 0xff800000
	s_waitcnt vmcnt(9)
	ds_write_b128 v26, v[0:3] offset:256
	s_waitcnt vmcnt(8)
	ds_write_b128 v26, v[4:7]
	s_waitcnt vmcnt(7)
	ds_write_b128 v26, v[8:11] offset:128
	s_waitcnt vmcnt(6)
	ds_write_b128 v20, v[12:15] offset:25600
	s_waitcnt vmcnt(5)
	ds_write_b128 v20, v[16:19] offset:25728
	v_or_b32_e32 v0, s35, v31
	v_mul_lo_u32 v215, v0, s4
	v_bfe_u32 v0, v30, 2, 2
	v_or3_b32 v0, v209, v0, s35
	v_mul_lo_u32 v210, v0, s38
	v_and_b32_e32 v0, 16, v30
	v_lshlrev_b32_e32 v1, 2, v30
	v_mov_b32_e32 v30, v129
	v_mov_b32_e32 v31, v129
	v_and_or_b32 v0, v1, 12, v0
	v_mov_b32_e32 v16, v129
	v_mov_b32_e32 v17, v129
	v_mov_b32_e32 v18, v129
	v_mov_b32_e32 v19, v129
	v_mov_b32_e32 v20, v129
	v_mov_b32_e32 v26, v129
	v_mov_b64_e32 v[46:47], v[30:31]
	v_mov_b64_e32 v[62:63], v[30:31]
	v_mov_b64_e32 v[78:79], v[30:31]
	v_lshlrev_b32_e32 v211, 1, v0
	v_mov_b64_e32 v[44:45], v[28:29]
	v_mov_b64_e32 v[42:43], v[26:27]
	v_mov_b64_e32 v[40:41], v[24:25]
	v_mov_b64_e32 v[38:39], v[22:23]
	v_mov_b64_e32 v[36:37], v[20:21]
	v_mov_b64_e32 v[34:35], v[18:19]
	v_mov_b64_e32 v[32:33], v[16:17]
	v_mov_b64_e32 v[60:61], v[28:29]
	v_mov_b64_e32 v[58:59], v[26:27]
	v_mov_b64_e32 v[56:57], v[24:25]
	v_mov_b64_e32 v[54:55], v[22:23]
	v_mov_b64_e32 v[52:53], v[20:21]
	v_mov_b64_e32 v[50:51], v[18:19]
	v_mov_b64_e32 v[48:49], v[16:17]
	v_mov_b64_e32 v[76:77], v[28:29]
	v_mov_b64_e32 v[74:75], v[26:27]
	v_mov_b64_e32 v[72:73], v[24:25]
	v_mov_b64_e32 v[70:71], v[22:23]
	v_mov_b64_e32 v[68:69], v[20:21]
	v_mov_b64_e32 v[66:67], v[18:19]
	v_mov_b64_e32 v[64:65], v[16:17]
	s_mov_b32 s4, 0
	s_waitcnt lgkmcnt(0)
	s_barrier

; DI int opaque_tid() { int t = threadIdx.x; asm volatile("" : "+v"(t)); return t; }
;     DI const bf16_t* Q() const { return (const bf16_t*)(ws + WS_Q); }
;     DI const bf16_t* KV() const { return (const bf16_t*)(ws + WS_KV); }
;     DI const bf16_t* KPE() const { return (const bf16_t*)(ws + WS_KPE); }
; #define MLA_LOAD() do { sreg[0] = *(const u32x4*)(kp0); sreg[1] = *(const u32x4*)(kp0 + 64); sreg[2] = *(const u32x4*)(kp0 + 128); sreg[3] = *(const u32x4*)(kp0 + 192); \
;         sreg[4] = *(const u32x4*)(kp1); kp0 += (size_t)64 * 2048; kp1 += (size_t)64 * 64; } while (0)
; #define MLA_WRITE(buf) do { LAS unsigned char* kd_ = lds + (buf) * BUFB + lkey * KSTR + lq * 16; LAS unsigned char* vd_ = lds + (buf) * BUFB + 64 * KSTR + lkey * VSTR + lq * 16; \
;         *(LAS u32x4*)(kd_) = sreg[0]; *(LAS u32x4*)(kd_ + 128) = sreg[1]; *(LAS u32x4*)(kd_ + 256) = sreg[4]; *(LAS u32x4*)(vd_) = sreg[2]; *(LAS u32x4*)(vd_ + 128) = sreg[3]; } while (0)
; template <bool ATOM>
; DI void mla_unit(LAS unsigned char* lds, const AttnPtrs& P, int b, int hd, int qb) {
;     ...
;     const int tid = opaque_tid(), lane = tid & 63, wid = __builtin_amdgcn_readfirstlane(tid >> 6), r = lane & 31, h = lane >> 5, rg = wid & 3, kh = wid >> 2;
;     const int fq_ = qb * 128 + rg * 32 + r;
;     const size_t tokq = (size_t)b * 2048 + fq_;
;     bf16x8 qf[NKK];
;     { const bf16_t* qp = P.Q() + tokq * 1536 + hd * 192;
; #pragma unroll
;       for (int kk = 0; kk < NKK; ++kk) qf[kk] = *(const bf16x8*)(qp + kk * 16 + 8 * h); }
;     f32x16 o[NDV];
; #pragma unroll
;     for (int d = 0; d < NDV; ++d)
; #pragma unroll
;         for (int i = 0; i < 16; ++i) o[d][i] = 0.f;
;     float mrun = -INFINITY, lrun = 0.f;
;     const int lkey = tid >> 3, lq = tid & 7;
;     const bf16_t* kp0 = P.KV() + ((size_t)b * 2048 + lkey) * 2048 + hd * 256 + lq * 8;
;     const bf16_t* kp1 = P.KPE() + ((size_t)b * 2048 + lkey) * 64 + lq * 8;
;     u32x4 sreg[5];
;     ...
;     const int nsteps = 2 * (qb + 1);
;     __syncthreads();
;     MLA_LOAD(); MLA_WRITE(0);
;     MLA_LOAD();
;     __syncthreads();
.LBB0_1074:
	v_mov_b32_e32 v30, v188
	s_xor_b32 s4, s16, 15
	s_lshl_b32 s19, s4, 7
	v_readfirstlane_b32 s16, v30
	s_bfe_u32 s18, s16, 0x20006
	s_lshl_b32 s14, s18, 5
	v_and_b32_e32 v31, 31, v30
	s_or_b32 s22, s14, s19
	v_or_b32_e32 v214, s22, v31
	v_or_b32_e32 v130, s50, v214
	s_waitcnt lgkmcnt(0)
	v_mov_b64_e32 v[0:1], s[10:11]
	v_mad_u64_u32 v[0:1], s[14:15], v130, s90, v[0:1]
	v_bfe_u32 v32, v30, 5, 1
	v_mad_i32_i24 v1, s51, v207, v1
	s_lshl_b32 s38, s17, 1
	v_lshl_add_u64 v[0:1], v[0:1], 0, s[38:39]
	v_lshlrev_b32_e32 v128, 4, v32
	v_lshl_add_u64 v[0:1], v[0:1], 0, v[128:129]
	global_load_dwordx4 v[180:183], v[0:1], off nt
	global_load_dwordx4 v[176:179], v[0:1], off offset:32 nt
	global_load_dwordx4 v[172:175], v[0:1], off offset:64 nt
	global_load_dwordx4 v[168:171], v[0:1], off offset:96 nt
	global_load_dwordx4 v[164:167], v[0:1], off offset:128 nt
	global_load_dwordx4 v[160:163], v[0:1], off offset:160 nt
	global_load_dwordx4 v[156:159], v[0:1], off offset:192 nt
	global_load_dwordx4 v[152:155], v[0:1], off offset:224 nt
	global_load_dwordx4 v[148:151], v[0:1], off offset:256 nt
	global_load_dwordx4 v[144:147], v[0:1], off offset:288 nt
	global_load_dwordx4 v[140:143], v[0:1], off offset:320 nt
	global_load_dwordx4 v[136:139], v[0:1], off offset:352 nt
	v_ashrrev_i32_e32 v20, 3, v30
	v_ashrrev_i32_e32 v21, 31, v20
	v_lshl_add_u64 v[0:1], s[50:51], 0, v[20:21]
	v_lshlrev_b64 v[2:3], 12, v[0:1]
	v_lshl_add_u64 v[2:3], s[12:13], 0, v[2:3]
	s_lshl_b32 s38, s48, 1
	v_lshlrev_b32_e32 v4, 4, v30
	v_lshlrev_b64 v[0:1], 7, v[0:1]
	v_lshl_add_u64 v[2:3], v[2:3], 0, s[38:39]
	v_and_b32_e32 v116, 0x70, v4
	v_mov_b32_e32 v117, v129
	v_lshl_add_u64 v[0:1], s[42:43], 0, v[0:1]
	v_lshl_add_u64 v[22:23], v[2:3], 0, v[116:117]
	v_lshl_add_u64 v[24:25], v[0:1], 0, v[116:117]
	s_barrier
	global_load_dwordx4 v[0:3], v[24:25], off
	global_load_dwordx4 v[4:7], v[22:23], off
	global_load_dwordx4 v[8:11], v[22:23], off offset:128
	global_load_dwordx4 v[12:15], v[22:23], off offset:256
	global_load_dwordx4 v[16:19], v[22:23], off offset:384
	v_add_co_u32_e32 v26, vcc, s89, v22
	s_movk_i32 s14, 0x2000
	s_nop 0
	v_addc_co_u32_e32 v27, vcc, 0, v23, vcc
	global_load_dwordx4 v[96:99], v[26:27], off
	global_load_dwordx4 v[100:103], v[26:27], off offset:128
	global_load_dwordx4 v[104:107], v[26:27], off offset:256
	v_add_co_u32_e32 v28, vcc, s14, v24
	s_lshl_b32 s15, s4, 1
	s_nop 0
	v_addc_co_u32_e32 v29, vcc, 0, v25, vcc
	global_load_dwordx4 v[108:111], v[26:27], off offset:384
	global_load_dwordx4 v[112:115], v[28:29], off
	s_movk_i32 s4, 0x190
	v_mul_lo_u32 v117, v20, s4
	v_bfe_u32 v27, v30, 2, 2
	s_movk_i32 s36, 0x120
	v_add3_u32 v26, 0, v117, v116
	s_movk_i32 s34, 0xff90
	s_ashr_i32 s17, s16, 8
	v_mul_lo_u32 v122, v20, s36
	v_mad_u64_u32 v[20:21], s[34:35], v20, s34, v[26:27]
	v_lshlrev_b32_e32 v209, 2, v32
	s_lshl_b32 s23, s17, 5
	s_mov_b64 s[34:35], 0x4000
	v_and_b32_e32 v208, 63, v30
	v_or_b32_e32 v21, s23, v31
	v_or3_b32 v27, v209, v27, s23
	v_lshl_add_u64 v[118:119], v[24:25], 0, s[34:35]
	s_mov_b64 s[34:35], 0x80000
	v_mov_b32_e32 v31, v129
	v_mul_lo_u32 v215, v21, s4
	v_mul_lo_u32 v210, v27, s36
	v_lshl_add_u64 v[120:121], v[22:23], 0, s[34:35]
	v_mov_b32_e32 v21, v129
	v_mov_b32_e32 v22, v129
	v_mov_b32_e32 v23, v129
	v_mov_b32_e32 v24, v129
	v_mov_b32_e32 v25, v129
	v_mov_b32_e32 v27, v129
	v_mov_b32_e32 v28, v129
	v_mov_b32_e32 v29, v129
	v_mov_b32_e32 v131, s51
	s_mov_b32 s14, 0
	s_or_b32 s34, s22, 31
	s_or_b32 s35, s19, 64
	v_or_b32_e32 v123, s23, v209
	v_mov_b32_e32 v213, 0
	v_mov_b32_e32 v124, 0xff800000
	s_mov_b32 s4, 0
	s_waitcnt vmcnt(9)
	ds_write_b128 v26, v[0:3] offset:256
	s_waitcnt vmcnt(8)
	ds_write_b128 v26, v[4:7]
	s_waitcnt vmcnt(7)
	ds_write_b128 v26, v[8:11] offset:128
	s_waitcnt vmcnt(6)
	ds_write_b128 v20, v[12:15] offset:25600
	s_waitcnt vmcnt(5)
	ds_write_b128 v20, v[16:19] offset:25728
	v_and_b32_e32 v0, 16, v30
	v_lshlrev_b32_e32 v1, 2, v30
	v_mov_b32_e32 v30, v129
	v_and_or_b32 v0, v1, 12, v0
	v_mov_b32_e32 v16, v129
	v_mov_b32_e32 v17, v129
	v_mov_b32_e32 v18, v129
	v_mov_b32_e32 v19, v129
	v_mov_b32_e32 v20, v129
	v_mov_b32_e32 v26, v129
	v_mov_b64_e32 v[46:47], v[30:31]
	v_mov_b64_e32 v[62:63], v[30:31]
	v_mov_b64_e32 v[78:79], v[30:31]
	v_lshlrev_b32_e32 v211, 1, v0
	v_mov_b64_e32 v[44:45], v[28:29]
	v_mov_b64_e32 v[42:43], v[26:27]
	v_mov_b64_e32 v[40:41], v[24:25]
	v_mov_b64_e32 v[38:39], v[22:23]
	v_mov_b64_e32 v[36:37], v[20:21]
	v_mov_b64_e32 v[34:35], v[18:19]
	v_mov_b64_e32 v[32:33], v[16:17]
	v_mov_b64_e32 v[60:61], v[28:29]
	v_mov_b64_e32 v[58:59], v[26:27]
	v_mov_b64_e32 v[56:57], v[24:25]
	v_mov_b64_e32 v[54:55], v[22:23]
	v_mov_b64_e32 v[52:53], v[20:21]
	v_mov_b64_e32 v[50:51], v[18:19]
	v_mov_b64_e32 v[48:49], v[16:17]
	v_mov_b64_e32 v[76:77], v[28:29]
	v_mov_b64_e32 v[74:75], v[26:27]
	v_mov_b64_e32 v[72:73], v[24:25]
	v_mov_b64_e32 v[70:71], v[22:23]
	v_mov_b64_e32 v[68:69], v[20:21]
	v_mov_b64_e32 v[66:67], v[18:19]
	v_mov_b64_e32 v[64:65], v[16:17]
	s_waitcnt lgkmcnt(0)
	s_barrier

; DI void ss_add(ssacc_t* p, float v) { atomicAdd(p, (ssacc_t)__float2ull_rn(v * 4294967296.f)); }
; DI float ss_get(const ssacc_t* p) { const ssacc_t v = *p; return (float)(unsigned)(v >> 32) + (float)(unsigned)(v & 0xffffffffull) * 2.3283064365386963e-10f; }
; DI float quad_sum(float s) { s += __shfl_xor(s, 16); s += __shfl_xor(s, 32); return s; }
; DI float sq8(const f32x4& a, const f32x4& b) { return (a[0] * a[0] + a[1] * a[1]) + (a[2] * a[2] + a[3] * a[3]) + (b[0] * b[0] + b[1] * b[1]) + (b[2] * b[2] + b[3] * b[3]); }
; DI u32x4 pack8(const f32x4& a, const f32x4& b) { u32x4 w; w.x = cvtpk(a[0], a[1]); w.y = cvtpk(a[2], a[3]); w.z = cvtpk(b[0], b[1]); w.w = cvtpk(b[2], b[3]); return w; }
;     DI void operator()(const Acc& acc, const Unit& u, int wr, int wc, int fr, int fq) const {
;     ...
;         for (int ai = 0; ai < 2; ++ai)
; #pragma unroll
;             for (int m = 0; m < 4; ++m) {
;                 asm volatile("" ::: "memory");
;                 const int row = u.pm * 256 + ai * 128 + wr * 64 + m * 16 + fr;
;                 const float rs = rsqrtf(ss_get(ss_dil + row) * (1.f / 512.f) + EPS_);
;                 float sq = 0.f;
; #pragma unroll
;                 for (int bj = 0; bj < 2; ++bj) {
;                     const size_t off = (size_t)row * 2048 + u.pn * 256 + bj * 128 + wc * 32 + 8 * fq;
;                     const f32x4 v0 = *(const f32x4*)(xin + off) + acc[ai][bj][m][0] * rs, v1 = *(const f32x4*)(xin + off + 4) + acc[ai][bj][m][1] * rs;
;                     *(f32x4*)(X + off) = v0; *(f32x4*)(X + off + 4) = v1; *(u32x4*)(XB + off) = pack8(v0, v1); sq += sq8(v0, v1);
;                 }
;                 sq = quad_sum(sq); if (fq == 0) ss_add(ssx1 + row, sq);
;             }
.LBB0_1278:
	v_lshl_add_u32 v146, s41, 8, v141
	v_ashrrev_i32_e32 v147, 31, v146
	v_lshl_add_u64 v[148:149], v[146:147], 3, s[56:57]
	global_load_dwordx2 v[208:209], v[148:149], off
	global_load_dwordx2 v[210:211], v[148:149], off offset:128
	global_load_dwordx2 v[212:213], v[148:149], off offset:256
	global_load_dwordx2 v[214:215], v[148:149], off offset:384
	global_load_dwordx2 v[216:217], v[148:149], off offset:1024
	global_load_dwordx2 v[218:219], v[148:149], off offset:1152
	global_load_dwordx2 v[220:221], v[148:149], off offset:1280
	global_load_dwordx2 v[222:223], v[148:149], off offset:1408
	s_min_u32 s16, s88, 32
	s_sub_i32 s17, 32, s16
	s_lshl_b32 s4, s40, 8
	s_ashr_i32 s14, s4, 31
	v_mov_b32_e32 v131, s14
	v_or_b32_e32 v130, s4, v140
	s_waitcnt vmcnt(7)
	v_mov_b32_e32 v148, v208
	v_mov_b32_e32 v149, v209
	v_mov_b32_e32 v128, v149
	v_lshlrev_b64 v[150:151], s16, v[128:129]
	v_min_u32_e32 v128, 1, v150
	v_or_b32_e32 v128, v151, v128
	v_cvt_f32_u32_e32 v128, v128
	v_cvt_f32_u32_e32 v148, v148
	v_ldexp_f32 v128, v128, s17
	v_fmac_f32_e32 v128, 0x2f800000, v148
	v_fmamk_f32 v128, v128, 0x3b000000, v195
	v_cmp_gt_f32_e32 vcc, s27, v128
	v_mul_f32_e32 v148, 0x4b800000, v128
	s_nop 0
	v_cndmask_b32_e32 v128, v128, v148, vcc
	v_rsq_f32_e32 v128, v128
	s_nop 0
	v_mul_f32_e32 v148, 0x45800000, v128
	v_cndmask_b32_e32 v128, v128, v148, vcc
	v_lshlrev_b64 v[148:149], 11, v[146:147]
	v_lshl_add_u64 v[148:149], v[148:149], 0, v[130:131]
	v_lshlrev_b64 v[164:165], 2, v[148:149]
	s_waitcnt lgkmcnt(0)
	v_lshl_add_u64 v[150:151], s[8:9], 0, v[164:165]
	global_load_dwordx4 v[156:159], v[150:151], off offset:16 nt
	global_load_dwordx4 v[160:163], v[150:151], off nt
	global_load_dwordx4 v[166:169], v[150:151], off offset:528 nt
	global_load_dwordx4 v[170:173], v[150:151], off offset:512 nt
	s_waitcnt vmcnt(3)
	v_pk_fma_f32 v[124:125], v[124:125], v[128:129], v[156:157] op_sel_hi:[1,0,1]
	s_waitcnt vmcnt(2)
	v_pk_fma_f32 v[122:123], v[122:123], v[128:129], v[162:163] op_sel_hi:[1,0,1]
	v_pk_fma_f32 v[120:121], v[120:121], v[128:129], v[160:161] op_sel_hi:[1,0,1]
	v_lshl_add_u64 v[156:157], s[60:61], 0, v[164:165]
	v_pk_fma_f32 v[126:127], v[126:127], v[128:129], v[158:159] op_sel_hi:[1,0,1]
	global_store_dwordx4 v[156:157], v[120:123], off
	global_store_dwordx4 v[156:157], v[124:127], off offset:16
	v_cvt_pk_bf16_f32 v156, v120, v121
	v_mul_f32_e32 v121, v121, v121
	v_fmac_f32_e32 v121, v120, v120
	v_mul_f32_e32 v120, v123, v123
	v_fmac_f32_e32 v120, v122, v122
	v_add_f32_e32 v120, v121, v120
	v_mul_f32_e32 v121, v125, v125
	v_fmac_f32_e32 v121, v124, v124
	v_cvt_pk_bf16_f32 v157, v122, v123
	v_cvt_pk_bf16_f32 v158, v124, v125
	v_cvt_pk_bf16_f32 v159, v126, v127
	v_lshl_add_u64 v[160:161], v[148:149], 1, s[62:63]
	v_add_f32_e32 v120, v121, v120
	v_mul_f32_e32 v121, v127, v127
	global_store_dwordx4 v[160:161], v[156:159], off
	v_fmac_f32_e32 v121, v126, v126
	v_add_f32_e32 v155, v121, v120
	v_or_b32_e32 v148, 0x80, v148
	s_waitcnt vmcnt(3)
	v_mov_b32_e32 v120, v166
	v_mov_b32_e32 v121, v167
	v_mov_b32_e32 v122, v168
	v_mov_b32_e32 v123, v169
	v_mov_b32_e32 v124, v170
	v_mov_b32_e32 v125, v171
	v_mov_b32_e32 v126, v172
	v_mov_b32_e32 v127, v173
	v_pk_fma_f32 v[116:117], v[116:117], v[128:129], v[120:121] op_sel_hi:[1,0,1]
	v_pk_fma_f32 v[114:115], v[114:115], v[128:129], v[126:127] op_sel_hi:[1,0,1]
	v_pk_fma_f32 v[112:113], v[112:113], v[128:129], v[124:125] op_sel_hi:[1,0,1]
	v_lshl_add_u64 v[120:121], v[148:149], 2, s[60:61]
	v_pk_fma_f32 v[118:119], v[118:119], v[128:129], v[122:123] op_sel_hi:[1,0,1]
	global_store_dwordx4 v[120:121], v[112:115], off
	global_store_dwordx4 v[120:121], v[116:119], off offset:16
	v_cvt_pk_bf16_f32 v120, v112, v113
	v_mul_f32_e32 v113, v113, v113
	v_fmac_f32_e32 v113, v112, v112
	v_mul_f32_e32 v112, v115, v115
	v_fmac_f32_e32 v112, v114, v114
	v_add_f32_e32 v112, v113, v112
	v_mul_f32_e32 v113, v117, v117
	v_fmac_f32_e32 v113, v116, v116
	v_add_f32_e32 v112, v113, v112
	v_mul_f32_e32 v113, v119, v119
	v_cvt_pk_bf16_f32 v121, v114, v115
	v_fmac_f32_e32 v113, v118, v118
	v_and_b32_e32 v114, 64, v199
	v_add_f32_e32 v112, v113, v112
	v_xor_b32_e32 v113, 16, v199
	v_add_u32_e32 v114, 64, v114
	v_cmp_lt_i32_e32 vcc, v113, v114
	v_add_f32_e32 v112, v155, v112
	v_cvt_pk_bf16_f32 v122, v116, v117
	v_cndmask_b32_e32 v113, v199, v113, vcc
	v_lshlrev_b32_e32 v115, 2, v113
	ds_bpermute_b32 v113, v115, v112
	v_cvt_pk_bf16_f32 v123, v118, v119
	v_lshl_add_u64 v[124:125], v[148:149], 1, s[62:63]
	global_store_dwordx4 v[124:125], v[120:123], off
	s_waitcnt lgkmcnt(0)
	v_add_f32_e32 v112, v112, v113
	v_xor_b32_e32 v113, 32, v199
	v_cmp_lt_i32_e32 vcc, v113, v114
	s_nop 1
	v_cndmask_b32_e32 v113, v199, v113, vcc
	v_lshlrev_b32_e32 v120, 2, v113
	ds_bpermute_b32 v113, v120, v112
	s_and_saveexec_b64 s[14:15], s[48:49]
	s_cbranch_execz .LBB0_1280
	s_waitcnt lgkmcnt(0)
	v_add_f32_e32 v112, v112, v113
	v_mul_f32_e32 v112, 0x4f800000, v112
	v_rndne_f32_e32 v112, v112
	v_mul_f32_e32 v113, 0x2f800000, v112
	v_floor_f32_e32 v113, v113
	v_fmac_f32_e32 v112, 0xcf800000, v113
	v_cvt_u32_f32_e32 v112, v112
	v_cvt_u32_f32_e32 v113, v113
	v_lshl_add_u64 v[224:225], v[146:147], 3, s[58:59]
	v_mov_b32_e32 v226, v112
	v_mov_b32_e32 v227, v113
; DI void ss_add(ssacc_t* p, float v) { atomicAdd(p, (ssacc_t)__float2ull_rn(v * 4294967296.f)); }
; DI float ss_get(const ssacc_t* p) { const ssacc_t v = *p; return (float)(unsigned)(v >> 32) + (float)(unsigned)(v & 0xffffffffull) * 2.3283064365386963e-10f; }
; DI float quad_sum(float s) { s += __shfl_xor(s, 16); s += __shfl_xor(s, 32); return s; }
; DI float sq8(const f32x4& a, const f32x4& b) { return (a[0] * a[0] + a[1] * a[1]) + (a[2] * a[2] + a[3] * a[3]) + (b[0] * b[0] + b[1] * b[1]) + (b[2] * b[2] + b[3] * b[3]); }
; DI u32x4 pack8(const f32x4& a, const f32x4& b) { u32x4 w; w.x = cvtpk(a[0], a[1]); w.y = cvtpk(a[2], a[3]); w.z = cvtpk(b[0], b[1]); w.w = cvtpk(b[2], b[3]); return w; }
;     DI void operator()(const Acc& acc, const Unit& u, int wr, int wc, int fr, int fq) const {
;     ...
;         for (int ai = 0; ai < 2; ++ai)
; #pragma unroll
;             for (int m = 0; m < 4; ++m) {
;                 asm volatile("" ::: "memory");
;                 const int row = u.pm * 256 + ai * 128 + wr * 64 + m * 16 + fr;
;                 const float rs = rsqrtf(ss_get(ss_dil + row) * (1.f / 512.f) + EPS_);
;                 float sq = 0.f;
; #pragma unroll
;                 for (int bj = 0; bj < 2; ++bj) {
;                     const size_t off = (size_t)row * 2048 + u.pn * 256 + bj * 128 + wc * 32 + 8 * fq;
;                     const f32x4 v0 = *(const f32x4*)(xin + off) + acc[ai][bj][m][0] * rs, v1 = *(const f32x4*)(xin + off + 4) + acc[ai][bj][m][1] * rs;
;                     *(f32x4*)(X + off) = v0; *(f32x4*)(X + off + 4) = v1; *(u32x4*)(XB + off) = pack8(v0, v1); sq += sq8(v0, v1);
;                 }
;                 sq = quad_sum(sq); if (fq == 0) ss_add(ssx1 + row, sq);
;             }
.LBB0_1280:
	s_or_b64 exec, exec, s[14:15]
	v_or_b32_e32 v112, 16, v146
	s_waitcnt lgkmcnt(0)
	v_ashrrev_i32_e32 v113, 31, v112
	s_waitcnt vmcnt(9)
	v_mov_b32_e32 v116, v210
	v_mov_b32_e32 v117, v211
	v_mov_b32_e32 v128, v117
	v_lshlrev_b64 v[118:119], s16, v[128:129]
	v_min_u32_e32 v114, 1, v118
	v_or_b32_e32 v114, v119, v114
	v_cvt_f32_u32_e32 v114, v114
	v_cvt_f32_u32_e32 v116, v116
	v_ldexp_f32 v114, v114, s17
	v_fmac_f32_e32 v114, 0x2f800000, v116
	v_fmamk_f32 v114, v114, 0x3b000000, v195
	v_cmp_gt_f32_e32 vcc, s27, v114
	v_mul_f32_e32 v116, 0x4b800000, v114
	s_nop 0
	v_cndmask_b32_e32 v114, v114, v116, vcc
	v_rsq_f32_e32 v114, v114
	s_nop 0
	v_mul_f32_e32 v116, 0x45800000, v114
	v_cndmask_b32_e32 v114, v114, v116, vcc
	v_lshlrev_b64 v[116:117], 11, v[112:113]
	v_lshl_add_u64 v[116:117], v[116:117], 0, v[130:131]
	v_lshlrev_b64 v[126:127], 2, v[116:117]
	v_lshl_add_u64 v[118:119], s[8:9], 0, v[126:127]
	global_load_dwordx4 v[122:125], v[118:119], off offset:16 nt
	global_load_dwordx4 v[148:151], v[118:119], off nt
	global_load_dwordx4 v[166:169], v[118:119], off offset:528 nt
	global_load_dwordx4 v[170:173], v[118:119], off offset:512 nt
	s_waitcnt vmcnt(3)
	v_pk_fma_f32 v[108:109], v[108:109], v[114:115], v[122:123] op_sel_hi:[1,0,1]
	s_waitcnt vmcnt(2)
	v_pk_fma_f32 v[106:107], v[106:107], v[114:115], v[150:151] op_sel_hi:[1,0,1]
	v_pk_fma_f32 v[104:105], v[104:105], v[114:115], v[148:149] op_sel_hi:[1,0,1]
	v_lshl_add_u64 v[122:123], s[60:61], 0, v[126:127]
	v_pk_fma_f32 v[110:111], v[110:111], v[114:115], v[124:125] op_sel_hi:[1,0,1]
	global_store_dwordx4 v[122:123], v[104:107], off
	global_store_dwordx4 v[122:123], v[108:111], off offset:16
	v_cvt_pk_bf16_f32 v122, v104, v105
	v_mul_f32_e32 v105, v105, v105
	v_fmac_f32_e32 v105, v104, v104
	v_mul_f32_e32 v104, v107, v107
	v_fmac_f32_e32 v104, v106, v106
	v_add_f32_e32 v104, v105, v104
	v_mul_f32_e32 v105, v109, v109
	v_fmac_f32_e32 v105, v108, v108
	v_cvt_pk_bf16_f32 v123, v106, v107
	v_cvt_pk_bf16_f32 v124, v108, v109
	v_cvt_pk_bf16_f32 v125, v110, v111
	v_lshl_add_u64 v[126:127], v[116:117], 1, s[62:63]
	v_add_f32_e32 v104, v105, v104
	v_mul_f32_e32 v105, v111, v111
	global_store_dwordx4 v[126:127], v[122:125], off
	v_fmac_f32_e32 v105, v110, v110
	v_add_f32_e32 v121, v105, v104
	v_or_b32_e32 v116, 0x80, v116
	s_waitcnt vmcnt(3)
	v_mov_b32_e32 v104, v166
	v_mov_b32_e32 v105, v167
	v_mov_b32_e32 v106, v168
	v_mov_b32_e32 v107, v169
	v_mov_b32_e32 v108, v170
	v_mov_b32_e32 v109, v171
	v_mov_b32_e32 v110, v172
	v_mov_b32_e32 v111, v173
	v_pk_fma_f32 v[100:101], v[100:101], v[114:115], v[104:105] op_sel_hi:[1,0,1]
	v_pk_fma_f32 v[98:99], v[98:99], v[114:115], v[110:111] op_sel_hi:[1,0,1]
	v_pk_fma_f32 v[96:97], v[96:97], v[114:115], v[108:109] op_sel_hi:[1,0,1]
	v_lshl_add_u64 v[104:105], v[116:117], 2, s[60:61]
	v_pk_fma_f32 v[102:103], v[102:103], v[114:115], v[106:107] op_sel_hi:[1,0,1]
	global_store_dwordx4 v[104:105], v[96:99], off
	global_store_dwordx4 v[104:105], v[100:103], off offset:16
	v_cvt_pk_bf16_f32 v104, v96, v97
	v_mul_f32_e32 v97, v97, v97
	v_fmac_f32_e32 v97, v96, v96
	v_mul_f32_e32 v96, v99, v99
	v_fmac_f32_e32 v96, v98, v98
	v_add_f32_e32 v96, v97, v96
	v_mul_f32_e32 v97, v101, v101
	v_fmac_f32_e32 v97, v100, v100
	v_add_f32_e32 v96, v97, v96
	v_mul_f32_e32 v97, v103, v103
	v_fmac_f32_e32 v97, v102, v102
	v_add_f32_e32 v96, v97, v96
	v_add_f32_e32 v96, v121, v96
	ds_bpermute_b32 v97, v115, v96
	v_cvt_pk_bf16_f32 v105, v98, v99
	v_cvt_pk_bf16_f32 v106, v100, v101
	v_cvt_pk_bf16_f32 v107, v102, v103
	v_lshl_add_u64 v[108:109], v[116:117], 1, s[62:63]
	s_waitcnt lgkmcnt(0)
	v_add_f32_e32 v96, v96, v97
	ds_bpermute_b32 v97, v120, v96
	global_store_dwordx4 v[108:109], v[104:107], off
	s_and_saveexec_b64 s[14:15], s[48:49]
	s_cbranch_execz .LBB0_1282
	s_waitcnt lgkmcnt(0)
	v_add_f32_e32 v96, v96, v97
	v_mul_f32_e32 v96, 0x4f800000, v96
	v_rndne_f32_e32 v96, v96
	v_mul_f32_e32 v97, 0x2f800000, v96
	v_floor_f32_e32 v97, v97
	v_fmac_f32_e32 v96, 0xcf800000, v97
	v_cvt_u32_f32_e32 v96, v96
	v_cvt_u32_f32_e32 v97, v97
	v_mov_b32_e32 v228, v96
	v_mov_b32_e32 v229, v97
.LBB0_1282:
	s_or_b64 exec, exec, s[14:15]
	v_or_b32_e32 v96, 32, v146
	s_waitcnt lgkmcnt(0)
	v_ashrrev_i32_e32 v97, 31, v96
	s_waitcnt vmcnt(11)
	v_mov_b32_e32 v98, v212
	v_mov_b32_e32 v99, v213
	v_mov_b32_e32 v128, v99
	v_lshlrev_b64 v[100:101], s16, v[128:129]
	v_min_u32_e32 v99, 1, v100
	v_or_b32_e32 v99, v101, v99
	v_lshlrev_b64 v[100:101], 11, v[96:97]
	v_lshl_add_u64 v[100:101], v[100:101], 0, v[130:131]
	v_lshlrev_b64 v[112:113], 2, v[100:101]
	v_lshl_add_u64 v[102:103], s[8:9], 0, v[112:113]
	global_load_dwordx4 v[104:107], v[102:103], off offset:16 nt
	global_load_dwordx4 v[108:111], v[102:103], off nt
	global_load_dwordx4 v[166:169], v[102:103], off offset:528 nt
	global_load_dwordx4 v[170:173], v[102:103], off offset:512 nt
	v_cvt_f32_u32_e32 v99, v99
	v_cvt_f32_u32_e32 v98, v98
	v_ldexp_f32 v99, v99, s17
	v_fmac_f32_e32 v99, 0x2f800000, v98
	v_fmamk_f32 v98, v99, 0x3b000000, v195
	v_cmp_gt_f32_e32 vcc, s27, v98
	v_mul_f32_e32 v99, 0x4b800000, v98
	s_nop 0
	v_cndmask_b32_e32 v98, v98, v99, vcc
	v_rsq_f32_e32 v98, v98
	s_nop 0
	v_mul_f32_e32 v99, 0x45800000, v98
	v_cndmask_b32_e32 v98, v98, v99, vcc
	s_waitcnt vmcnt(3)
	v_pk_fma_f32 v[92:93], v[92:93], v[98:99], v[104:105] op_sel_hi:[1,0,1]
	s_waitcnt vmcnt(2)
; DI void ss_add(ssacc_t* p, float v) { atomicAdd(p, (ssacc_t)__float2ull_rn(v * 4294967296.f)); }
; DI float ss_get(const ssacc_t* p) { const ssacc_t v = *p; return (float)(unsigned)(v >> 32) + (float)(unsigned)(v & 0xffffffffull) * 2.3283064365386963e-10f; }
; DI float quad_sum(float s) { s += __shfl_xor(s, 16); s += __shfl_xor(s, 32); return s; }
; DI float sq8(const f32x4& a, const f32x4& b) { return (a[0] * a[0] + a[1] * a[1]) + (a[2] * a[2] + a[3] * a[3]) + (b[0] * b[0] + b[1] * b[1]) + (b[2] * b[2] + b[3] * b[3]); }
; DI u32x4 pack8(const f32x4& a, const f32x4& b) { u32x4 w; w.x = cvtpk(a[0], a[1]); w.y = cvtpk(a[2], a[3]); w.z = cvtpk(b[0], b[1]); w.w = cvtpk(b[2], b[3]); return w; }
;     DI void operator()(const Acc& acc, const Unit& u, int wr, int wc, int fr, int fq) const {
;     ...
;             for (int m = 0; m < 4; ++m) {
;                 asm volatile("" ::: "memory");
;                 const int row = u.pm * 256 + ai * 128 + wr * 64 + m * 16 + fr;
;                 const float rs = rsqrtf(ss_get(ss_dil + row) * (1.f / 512.f) + EPS_);
;                 float sq = 0.f;
; #pragma unroll
;                 for (int bj = 0; bj < 2; ++bj) {
;                     const size_t off = (size_t)row * 2048 + u.pn * 256 + bj * 128 + wc * 32 + 8 * fq;
;                     const f32x4 v0 = *(const f32x4*)(xin + off) + acc[ai][bj][m][0] * rs, v1 = *(const f32x4*)(xin + off + 4) + acc[ai][bj][m][1] * rs;
;                     *(f32x4*)(X + off) = v0; *(f32x4*)(X + off + 4) = v1; *(u32x4*)(XB + off) = pack8(v0, v1); sq += sq8(v0, v1);
;                 }
;                 sq = quad_sum(sq); if (fq == 0) ss_add(ssx1 + row, sq);
;             }
	v_pk_fma_f32 v[90:91], v[90:91], v[98:99], v[110:111] op_sel_hi:[1,0,1]
	v_pk_fma_f32 v[88:89], v[88:89], v[98:99], v[108:109] op_sel_hi:[1,0,1]
	v_lshl_add_u64 v[104:105], s[60:61], 0, v[112:113]
	v_pk_fma_f32 v[94:95], v[94:95], v[98:99], v[106:107] op_sel_hi:[1,0,1]
	global_store_dwordx4 v[104:105], v[88:91], off
	global_store_dwordx4 v[104:105], v[92:95], off offset:16
	v_cvt_pk_bf16_f32 v104, v88, v89
	v_mul_f32_e32 v89, v89, v89
	v_fmac_f32_e32 v89, v88, v88
	v_mul_f32_e32 v88, v91, v91
	v_fmac_f32_e32 v88, v90, v90
	v_add_f32_e32 v88, v89, v88
	v_mul_f32_e32 v89, v93, v93
	v_fmac_f32_e32 v89, v92, v92
	v_cvt_pk_bf16_f32 v105, v90, v91
	v_cvt_pk_bf16_f32 v106, v92, v93
	v_cvt_pk_bf16_f32 v107, v94, v95
	v_lshl_add_u64 v[108:109], v[100:101], 1, s[62:63]
	v_add_f32_e32 v88, v89, v88
	v_mul_f32_e32 v89, v95, v95
	global_store_dwordx4 v[108:109], v[104:107], off
	v_fmac_f32_e32 v89, v94, v94
	v_add_f32_e32 v99, v89, v88
	v_or_b32_e32 v100, 0x80, v100
	s_waitcnt vmcnt(3)
	v_mov_b32_e32 v88, v166
	v_mov_b32_e32 v89, v167
	v_mov_b32_e32 v90, v168
	v_mov_b32_e32 v91, v169
	v_mov_b32_e32 v92, v170
	v_mov_b32_e32 v93, v171
	v_mov_b32_e32 v94, v172
	v_mov_b32_e32 v95, v173
	v_pk_fma_f32 v[84:85], v[84:85], v[98:99], v[88:89] op_sel_hi:[1,0,1]
	v_pk_fma_f32 v[82:83], v[82:83], v[98:99], v[94:95] op_sel_hi:[1,0,1]
	v_pk_fma_f32 v[80:81], v[80:81], v[98:99], v[92:93] op_sel_hi:[1,0,1]
	v_lshl_add_u64 v[88:89], v[100:101], 2, s[60:61]
	v_pk_fma_f32 v[86:87], v[86:87], v[98:99], v[90:91] op_sel_hi:[1,0,1]
	global_store_dwordx4 v[88:89], v[80:83], off
	global_store_dwordx4 v[88:89], v[84:87], off offset:16
	v_cvt_pk_bf16_f32 v88, v80, v81
	v_mul_f32_e32 v81, v81, v81
	v_fmac_f32_e32 v81, v80, v80
	v_mul_f32_e32 v80, v83, v83
	v_fmac_f32_e32 v80, v82, v82
	v_add_f32_e32 v80, v81, v80
	v_mul_f32_e32 v81, v85, v85
	v_fmac_f32_e32 v81, v84, v84
	v_add_f32_e32 v80, v81, v80
	v_mul_f32_e32 v81, v87, v87
	v_fmac_f32_e32 v81, v86, v86
	v_add_f32_e32 v80, v81, v80
	v_add_f32_e32 v80, v99, v80
	ds_bpermute_b32 v81, v115, v80
	v_cvt_pk_bf16_f32 v89, v82, v83
	v_cvt_pk_bf16_f32 v90, v84, v85
	v_cvt_pk_bf16_f32 v91, v86, v87
	v_lshl_add_u64 v[92:93], v[100:101], 1, s[62:63]
	s_waitcnt lgkmcnt(0)
	v_add_f32_e32 v80, v80, v81
	ds_bpermute_b32 v81, v120, v80
	global_store_dwordx4 v[92:93], v[88:91], off
	s_and_saveexec_b64 s[14:15], s[48:49]
	s_cbranch_execz .LBB0_1284
	s_waitcnt lgkmcnt(0)
	v_add_f32_e32 v80, v80, v81
	v_mul_f32_e32 v80, 0x4f800000, v80
	v_rndne_f32_e32 v80, v80
	v_mul_f32_e32 v81, 0x2f800000, v80
	v_floor_f32_e32 v81, v81
	v_fmac_f32_e32 v80, 0xcf800000, v81
	v_cvt_u32_f32_e32 v80, v80
	v_cvt_u32_f32_e32 v81, v81
	v_mov_b32_e32 v230, v80
	v_mov_b32_e32 v231, v81
.LBB0_1284:
	s_or_b64 exec, exec, s[14:15]
	v_or_b32_e32 v80, 48, v146
	s_waitcnt lgkmcnt(0)
	v_ashrrev_i32_e32 v81, 31, v80
	s_waitcnt vmcnt(13)
	v_mov_b32_e32 v82, v214
	v_mov_b32_e32 v83, v215
	v_mov_b32_e32 v128, v83
	v_lshlrev_b64 v[84:85], s16, v[128:129]
	v_min_u32_e32 v83, 1, v84
	v_or_b32_e32 v83, v85, v83
	v_lshlrev_b64 v[84:85], 11, v[80:81]
	v_lshl_add_u64 v[84:85], v[84:85], 0, v[130:131]
	v_lshlrev_b64 v[96:97], 2, v[84:85]
	v_lshl_add_u64 v[86:87], s[8:9], 0, v[96:97]
	global_load_dwordx4 v[88:91], v[86:87], off offset:16 nt
	global_load_dwordx4 v[92:95], v[86:87], off nt
	global_load_dwordx4 v[166:169], v[86:87], off offset:528 nt
	global_load_dwordx4 v[170:173], v[86:87], off offset:512 nt
	v_cvt_f32_u32_e32 v83, v83
	v_cvt_f32_u32_e32 v82, v82
	v_ldexp_f32 v83, v83, s17
	v_fmac_f32_e32 v83, 0x2f800000, v82
	v_fmamk_f32 v82, v83, 0x3b000000, v195
	v_cmp_gt_f32_e32 vcc, s27, v82
	v_mul_f32_e32 v83, 0x4b800000, v82
	s_nop 0
	v_cndmask_b32_e32 v82, v82, v83, vcc
	v_rsq_f32_e32 v82, v82
	s_nop 0
	v_mul_f32_e32 v83, 0x45800000, v82
	v_cndmask_b32_e32 v82, v82, v83, vcc
	s_waitcnt vmcnt(3)
	v_pk_fma_f32 v[76:77], v[76:77], v[82:83], v[88:89] op_sel_hi:[1,0,1]
	s_waitcnt vmcnt(2)
	v_pk_fma_f32 v[74:75], v[74:75], v[82:83], v[94:95] op_sel_hi:[1,0,1]
	v_pk_fma_f32 v[72:73], v[72:73], v[82:83], v[92:93] op_sel_hi:[1,0,1]
	v_lshl_add_u64 v[88:89], s[60:61], 0, v[96:97]
	v_pk_fma_f32 v[78:79], v[78:79], v[82:83], v[90:91] op_sel_hi:[1,0,1]
	global_store_dwordx4 v[88:89], v[72:75], off
	global_store_dwordx4 v[88:89], v[76:79], off offset:16
	v_cvt_pk_bf16_f32 v88, v72, v73
	v_mul_f32_e32 v73, v73, v73
	v_fmac_f32_e32 v73, v72, v72
	v_mul_f32_e32 v72, v75, v75
	v_fmac_f32_e32 v72, v74, v74
	v_add_f32_e32 v72, v73, v72
	v_mul_f32_e32 v73, v77, v77
	v_fmac_f32_e32 v73, v76, v76
	v_cvt_pk_bf16_f32 v89, v74, v75
	v_cvt_pk_bf16_f32 v90, v76, v77
	v_cvt_pk_bf16_f32 v91, v78, v79
	v_lshl_add_u64 v[92:93], v[84:85], 1, s[62:63]
	v_add_f32_e32 v72, v73, v72
	v_mul_f32_e32 v73, v79, v79
	global_store_dwordx4 v[92:93], v[88:91], off
	v_fmac_f32_e32 v73, v78, v78
	v_add_f32_e32 v83, v73, v72
	v_or_b32_e32 v84, 0x80, v84
	s_waitcnt vmcnt(3)
	v_mov_b32_e32 v72, v166
	v_mov_b32_e32 v73, v167
	v_mov_b32_e32 v74, v168
	v_mov_b32_e32 v75, v169
	v_mov_b32_e32 v76, v170
	v_mov_b32_e32 v77, v171
	v_mov_b32_e32 v78, v172
	v_mov_b32_e32 v79, v173
	v_pk_fma_f32 v[68:69], v[68:69], v[82:83], v[72:73] op_sel_hi:[1,0,1]
	v_pk_fma_f32 v[66:67], v[66:67], v[82:83], v[78:79] op_sel_hi:[1,0,1]
	v_pk_fma_f32 v[64:65], v[64:65], v[82:83], v[76:77] op_sel_hi:[1,0,1]
	v_lshl_add_u64 v[72:73], v[84:85], 2, s[60:61]
	v_pk_fma_f32 v[70:71], v[70:71], v[82:83], v[74:75] op_sel_hi:[1,0,1]
	global_store_dwordx4 v[72:73], v[64:67], off
	global_store_dwordx4 v[72:73], v[68:71], off offset:16
	v_cvt_pk_bf16_f32 v72, v64, v65
	v_mul_f32_e32 v65, v65, v65
	v_fmac_f32_e32 v65, v64, v64
	v_mul_f32_e32 v64, v67, v67
	v_fmac_f32_e32 v64, v66, v66
	v_add_f32_e32 v64, v65, v64
	v_mul_f32_e32 v65, v69, v69
	v_fmac_f32_e32 v65, v68, v68
	v_add_f32_e32 v64, v65, v64
	v_mul_f32_e32 v65, v71, v71
	v_fmac_f32_e32 v65, v70, v70
	v_add_f32_e32 v64, v65, v64
	v_add_f32_e32 v64, v83, v64
	ds_bpermute_b32 v65, v115, v64
	v_cvt_pk_bf16_f32 v73, v66, v67
	v_cvt_pk_bf16_f32 v74, v68, v69
	v_cvt_pk_bf16_f32 v75, v70, v71
	v_lshl_add_u64 v[76:77], v[84:85], 1, s[62:63]
	s_waitcnt lgkmcnt(0)
	v_add_f32_e32 v64, v64, v65
	ds_bpermute_b32 v65, v120, v64
	global_store_dwordx4 v[76:77], v[72:75], off
	s_and_saveexec_b64 s[14:15], s[48:49]
	s_cbranch_execz .LBB0_1286
	s_waitcnt lgkmcnt(0)
	v_add_f32_e32 v64, v64, v65
	v_mul_f32_e32 v64, 0x4f800000, v64
	v_rndne_f32_e32 v64, v64
	v_mul_f32_e32 v65, 0x2f800000, v64
	v_floor_f32_e32 v65, v65
	v_fmac_f32_e32 v64, 0xcf800000, v65
	v_cvt_u32_f32_e32 v64, v64
	v_cvt_u32_f32_e32 v65, v65
	v_mov_b32_e32 v232, v64
	v_mov_b32_e32 v233, v65
; DI void ss_add(ssacc_t* p, float v) { atomicAdd(p, (ssacc_t)__float2ull_rn(v * 4294967296.f)); }
; DI float ss_get(const ssacc_t* p) { const ssacc_t v = *p; return (float)(unsigned)(v >> 32) + (float)(unsigned)(v & 0xffffffffull) * 2.3283064365386963e-10f; }
; DI float quad_sum(float s) { s += __shfl_xor(s, 16); s += __shfl_xor(s, 32); return s; }
; DI float sq8(const f32x4& a, const f32x4& b) { return (a[0] * a[0] + a[1] * a[1]) + (a[2] * a[2] + a[3] * a[3]) + (b[0] * b[0] + b[1] * b[1]) + (b[2] * b[2] + b[3] * b[3]); }
; DI u32x4 pack8(const f32x4& a, const f32x4& b) { u32x4 w; w.x = cvtpk(a[0], a[1]); w.y = cvtpk(a[2], a[3]); w.z = cvtpk(b[0], b[1]); w.w = cvtpk(b[2], b[3]); return w; }
;     DI void operator()(const Acc& acc, const Unit& u, int wr, int wc, int fr, int fq) const {
;     ...
;             for (int m = 0; m < 4; ++m) {
;                 asm volatile("" ::: "memory");
;                 const int row = u.pm * 256 + ai * 128 + wr * 64 + m * 16 + fr;
;                 const float rs = rsqrtf(ss_get(ss_dil + row) * (1.f / 512.f) + EPS_);
;                 float sq = 0.f;
; #pragma unroll
;                 for (int bj = 0; bj < 2; ++bj) {
;                     const size_t off = (size_t)row * 2048 + u.pn * 256 + bj * 128 + wc * 32 + 8 * fq;
;                     const f32x4 v0 = *(const f32x4*)(xin + off) + acc[ai][bj][m][0] * rs, v1 = *(const f32x4*)(xin + off + 4) + acc[ai][bj][m][1] * rs;
;                     *(f32x4*)(X + off) = v0; *(f32x4*)(X + off + 4) = v1; *(u32x4*)(XB + off) = pack8(v0, v1); sq += sq8(v0, v1);
;                 }
;                 sq = quad_sum(sq); if (fq == 0) ss_add(ssx1 + row, sq);
;             }
.LBB0_1286:
	s_or_b64 exec, exec, s[14:15]
	v_add_u32_e32 v64, 0x80, v146
	s_waitcnt lgkmcnt(0)
	v_ashrrev_i32_e32 v65, 31, v64
	s_waitcnt vmcnt(15)
	v_mov_b32_e32 v66, v216
	v_mov_b32_e32 v67, v217
	v_mov_b32_e32 v128, v67
	v_lshlrev_b64 v[68:69], s16, v[128:129]
	v_min_u32_e32 v67, 1, v68
	v_or_b32_e32 v67, v69, v67
	v_lshlrev_b64 v[68:69], 11, v[64:65]
	v_lshl_add_u64 v[68:69], v[68:69], 0, v[130:131]
	v_lshlrev_b64 v[80:81], 2, v[68:69]
	v_lshl_add_u64 v[70:71], s[8:9], 0, v[80:81]
	global_load_dwordx4 v[72:75], v[70:71], off offset:16 nt
	global_load_dwordx4 v[76:79], v[70:71], off nt
	global_load_dwordx4 v[166:169], v[70:71], off offset:528 nt
	global_load_dwordx4 v[170:173], v[70:71], off offset:512 nt
	v_cvt_f32_u32_e32 v67, v67
	v_cvt_f32_u32_e32 v66, v66
	v_ldexp_f32 v67, v67, s17
	v_fmac_f32_e32 v67, 0x2f800000, v66
	v_fmamk_f32 v66, v67, 0x3b000000, v195
	v_cmp_gt_f32_e32 vcc, s27, v66
	v_mul_f32_e32 v67, 0x4b800000, v66
	s_nop 0
	v_cndmask_b32_e32 v66, v66, v67, vcc
	v_rsq_f32_e32 v66, v66
	s_nop 0
	v_mul_f32_e32 v67, 0x45800000, v66
	v_cndmask_b32_e32 v66, v66, v67, vcc
	s_waitcnt vmcnt(3)
	v_pk_fma_f32 v[60:61], v[60:61], v[66:67], v[72:73] op_sel_hi:[1,0,1]
	s_waitcnt vmcnt(2)
	v_pk_fma_f32 v[58:59], v[58:59], v[66:67], v[78:79] op_sel_hi:[1,0,1]
	v_pk_fma_f32 v[56:57], v[56:57], v[66:67], v[76:77] op_sel_hi:[1,0,1]
	v_lshl_add_u64 v[72:73], s[60:61], 0, v[80:81]
	v_pk_fma_f32 v[62:63], v[62:63], v[66:67], v[74:75] op_sel_hi:[1,0,1]
	global_store_dwordx4 v[72:73], v[56:59], off
	global_store_dwordx4 v[72:73], v[60:63], off offset:16
	v_cvt_pk_bf16_f32 v72, v56, v57
	v_mul_f32_e32 v57, v57, v57
	v_fmac_f32_e32 v57, v56, v56
	v_mul_f32_e32 v56, v59, v59
	v_fmac_f32_e32 v56, v58, v58
	v_add_f32_e32 v56, v57, v56
	v_mul_f32_e32 v57, v61, v61
	v_fmac_f32_e32 v57, v60, v60
	v_cvt_pk_bf16_f32 v73, v58, v59
	v_cvt_pk_bf16_f32 v74, v60, v61
	v_cvt_pk_bf16_f32 v75, v62, v63
	v_lshl_add_u64 v[76:77], v[68:69], 1, s[62:63]
	v_add_f32_e32 v56, v57, v56
	v_mul_f32_e32 v57, v63, v63
	global_store_dwordx4 v[76:77], v[72:75], off
	v_fmac_f32_e32 v57, v62, v62
	v_add_f32_e32 v67, v57, v56
	v_or_b32_e32 v68, 0x80, v68
	s_waitcnt vmcnt(3)
	v_mov_b32_e32 v56, v166
	v_mov_b32_e32 v57, v167
	v_mov_b32_e32 v58, v168
	v_mov_b32_e32 v59, v169
	v_mov_b32_e32 v60, v170
	v_mov_b32_e32 v61, v171
	v_mov_b32_e32 v62, v172
	v_mov_b32_e32 v63, v173
	v_pk_fma_f32 v[52:53], v[52:53], v[66:67], v[56:57] op_sel_hi:[1,0,1]
	v_pk_fma_f32 v[50:51], v[50:51], v[66:67], v[62:63] op_sel_hi:[1,0,1]
	v_pk_fma_f32 v[48:49], v[48:49], v[66:67], v[60:61] op_sel_hi:[1,0,1]
	v_lshl_add_u64 v[56:57], v[68:69], 2, s[60:61]
	v_pk_fma_f32 v[54:55], v[54:55], v[66:67], v[58:59] op_sel_hi:[1,0,1]
	global_store_dwordx4 v[56:57], v[48:51], off
	global_store_dwordx4 v[56:57], v[52:55], off offset:16
	v_cvt_pk_bf16_f32 v56, v48, v49
	v_mul_f32_e32 v49, v49, v49
	v_fmac_f32_e32 v49, v48, v48
	v_mul_f32_e32 v48, v51, v51
	v_fmac_f32_e32 v48, v50, v50
	v_add_f32_e32 v48, v49, v48
	v_mul_f32_e32 v49, v53, v53
	v_fmac_f32_e32 v49, v52, v52
	v_add_f32_e32 v48, v49, v48
	v_mul_f32_e32 v49, v55, v55
	v_fmac_f32_e32 v49, v54, v54
	v_add_f32_e32 v48, v49, v48
	v_add_f32_e32 v48, v67, v48
	ds_bpermute_b32 v49, v115, v48
	v_cvt_pk_bf16_f32 v57, v50, v51
	v_cvt_pk_bf16_f32 v58, v52, v53
	v_cvt_pk_bf16_f32 v59, v54, v55
	v_lshl_add_u64 v[60:61], v[68:69], 1, s[62:63]
	s_waitcnt lgkmcnt(0)
	v_add_f32_e32 v48, v48, v49
	ds_bpermute_b32 v49, v120, v48
	global_store_dwordx4 v[60:61], v[56:59], off
	s_and_saveexec_b64 s[14:15], s[48:49]
	s_cbranch_execz .LBB0_1288
	s_waitcnt lgkmcnt(0)
	v_add_f32_e32 v48, v48, v49
	v_mul_f32_e32 v48, 0x4f800000, v48
	v_rndne_f32_e32 v48, v48
	v_mul_f32_e32 v49, 0x2f800000, v48
	v_floor_f32_e32 v49, v49
	v_fmac_f32_e32 v48, 0xcf800000, v49
	v_cvt_u32_f32_e32 v48, v48
	v_cvt_u32_f32_e32 v49, v49
	v_mov_b32_e32 v234, v48
	v_mov_b32_e32 v235, v49
.LBB0_1288:
	s_or_b64 exec, exec, s[14:15]
	v_add_u32_e32 v48, 0x90, v146
	s_waitcnt lgkmcnt(0)
	v_ashrrev_i32_e32 v49, 31, v48
	s_waitcnt vmcnt(17)
	v_mov_b32_e32 v50, v218
	v_mov_b32_e32 v51, v219
	v_mov_b32_e32 v128, v51
	v_lshlrev_b64 v[52:53], s16, v[128:129]
	v_min_u32_e32 v51, 1, v52
	v_or_b32_e32 v51, v53, v51
	v_lshlrev_b64 v[52:53], 11, v[48:49]
	v_lshl_add_u64 v[52:53], v[52:53], 0, v[130:131]
	v_lshlrev_b64 v[64:65], 2, v[52:53]
	v_lshl_add_u64 v[54:55], s[8:9], 0, v[64:65]
	global_load_dwordx4 v[56:59], v[54:55], off offset:16 nt
	global_load_dwordx4 v[60:63], v[54:55], off nt
	global_load_dwordx4 v[166:169], v[54:55], off offset:528 nt
	global_load_dwordx4 v[170:173], v[54:55], off offset:512 nt
	v_cvt_f32_u32_e32 v51, v51
	v_cvt_f32_u32_e32 v50, v50
	v_ldexp_f32 v51, v51, s17
	v_fmac_f32_e32 v51, 0x2f800000, v50
	v_fmamk_f32 v50, v51, 0x3b000000, v195
	v_cmp_gt_f32_e32 vcc, s27, v50
	v_mul_f32_e32 v51, 0x4b800000, v50
	s_nop 0
	v_cndmask_b32_e32 v50, v50, v51, vcc
	v_rsq_f32_e32 v50, v50
	s_nop 0
	v_mul_f32_e32 v51, 0x45800000, v50
	v_cndmask_b32_e32 v50, v50, v51, vcc
	s_waitcnt vmcnt(3)
	v_pk_fma_f32 v[44:45], v[44:45], v[50:51], v[56:57] op_sel_hi:[1,0,1]
	s_waitcnt vmcnt(2)
	v_pk_fma_f32 v[42:43], v[42:43], v[50:51], v[62:63] op_sel_hi:[1,0,1]
	v_pk_fma_f32 v[40:41], v[40:41], v[50:51], v[60:61] op_sel_hi:[1,0,1]
	v_lshl_add_u64 v[56:57], s[60:61], 0, v[64:65]
	v_pk_fma_f32 v[46:47], v[46:47], v[50:51], v[58:59] op_sel_hi:[1,0,1]
	global_store_dwordx4 v[56:57], v[40:43], off
	global_store_dwordx4 v[56:57], v[44:47], off offset:16
	v_cvt_pk_bf16_f32 v56, v40, v41
	v_mul_f32_e32 v41, v41, v41
	v_fmac_f32_e32 v41, v40, v40
	v_mul_f32_e32 v40, v43, v43
	v_fmac_f32_e32 v40, v42, v42
	v_add_f32_e32 v40, v41, v40
	v_mul_f32_e32 v41, v45, v45
	v_fmac_f32_e32 v41, v44, v44
	v_cvt_pk_bf16_f32 v57, v42, v43
	v_cvt_pk_bf16_f32 v58, v44, v45
	v_cvt_pk_bf16_f32 v59, v46, v47
	v_lshl_add_u64 v[60:61], v[52:53], 1, s[62:63]
	v_add_f32_e32 v40, v41, v40
	v_mul_f32_e32 v41, v47, v47
	global_store_dwordx4 v[60:61], v[56:59], off
	v_fmac_f32_e32 v41, v46, v46
	v_add_f32_e32 v51, v41, v40
	v_or_b32_e32 v52, 0x80, v52
	s_waitcnt vmcnt(3)
; DI void ss_add(ssacc_t* p, float v) { atomicAdd(p, (ssacc_t)__float2ull_rn(v * 4294967296.f)); }
; DI float ss_get(const ssacc_t* p) { const ssacc_t v = *p; return (float)(unsigned)(v >> 32) + (float)(unsigned)(v & 0xffffffffull) * 2.3283064365386963e-10f; }
; DI float quad_sum(float s) { s += __shfl_xor(s, 16); s += __shfl_xor(s, 32); return s; }
; DI float sq8(const f32x4& a, const f32x4& b) { return (a[0] * a[0] + a[1] * a[1]) + (a[2] * a[2] + a[3] * a[3]) + (b[0] * b[0] + b[1] * b[1]) + (b[2] * b[2] + b[3] * b[3]); }
; DI u32x4 pack8(const f32x4& a, const f32x4& b) { u32x4 w; w.x = cvtpk(a[0], a[1]); w.y = cvtpk(a[2], a[3]); w.z = cvtpk(b[0], b[1]); w.w = cvtpk(b[2], b[3]); return w; }
;     DI void operator()(const Acc& acc, const Unit& u, int wr, int wc, int fr, int fq) const {
;     ...
;             for (int m = 0; m < 4; ++m) {
;                 asm volatile("" ::: "memory");
;                 const int row = u.pm * 256 + ai * 128 + wr * 64 + m * 16 + fr;
;                 const float rs = rsqrtf(ss_get(ss_dil + row) * (1.f / 512.f) + EPS_);
;                 float sq = 0.f;
; #pragma unroll
;                 for (int bj = 0; bj < 2; ++bj) {
;                     const size_t off = (size_t)row * 2048 + u.pn * 256 + bj * 128 + wc * 32 + 8 * fq;
;                     const f32x4 v0 = *(const f32x4*)(xin + off) + acc[ai][bj][m][0] * rs, v1 = *(const f32x4*)(xin + off + 4) + acc[ai][bj][m][1] * rs;
;                     *(f32x4*)(X + off) = v0; *(f32x4*)(X + off + 4) = v1; *(u32x4*)(XB + off) = pack8(v0, v1); sq += sq8(v0, v1);
;                 }
;                 sq = quad_sum(sq); if (fq == 0) ss_add(ssx1 + row, sq);
;             }
	v_mov_b32_e32 v40, v166
	v_mov_b32_e32 v41, v167
	v_mov_b32_e32 v42, v168
	v_mov_b32_e32 v43, v169
	v_mov_b32_e32 v44, v170
	v_mov_b32_e32 v45, v171
	v_mov_b32_e32 v46, v172
	v_mov_b32_e32 v47, v173
	v_pk_fma_f32 v[36:37], v[36:37], v[50:51], v[40:41] op_sel_hi:[1,0,1]
	v_pk_fma_f32 v[34:35], v[34:35], v[50:51], v[46:47] op_sel_hi:[1,0,1]
	v_pk_fma_f32 v[32:33], v[32:33], v[50:51], v[44:45] op_sel_hi:[1,0,1]
	v_lshl_add_u64 v[40:41], v[52:53], 2, s[60:61]
	v_pk_fma_f32 v[38:39], v[38:39], v[50:51], v[42:43] op_sel_hi:[1,0,1]
	global_store_dwordx4 v[40:41], v[32:35], off
	global_store_dwordx4 v[40:41], v[36:39], off offset:16
	v_cvt_pk_bf16_f32 v40, v32, v33
	v_mul_f32_e32 v33, v33, v33
	v_fmac_f32_e32 v33, v32, v32
	v_mul_f32_e32 v32, v35, v35
	v_fmac_f32_e32 v32, v34, v34
	v_add_f32_e32 v32, v33, v32
	v_mul_f32_e32 v33, v37, v37
	v_fmac_f32_e32 v33, v36, v36
	v_add_f32_e32 v32, v33, v32
	v_mul_f32_e32 v33, v39, v39
	v_fmac_f32_e32 v33, v38, v38
	v_add_f32_e32 v32, v33, v32
	v_add_f32_e32 v32, v51, v32
	ds_bpermute_b32 v33, v115, v32
	v_cvt_pk_bf16_f32 v41, v34, v35
	v_cvt_pk_bf16_f32 v42, v36, v37
	v_cvt_pk_bf16_f32 v43, v38, v39
	v_lshl_add_u64 v[44:45], v[52:53], 1, s[62:63]
	s_waitcnt lgkmcnt(0)
	v_add_f32_e32 v32, v32, v33
	ds_bpermute_b32 v33, v120, v32
	global_store_dwordx4 v[44:45], v[40:43], off
	s_and_saveexec_b64 s[14:15], s[48:49]
	s_cbranch_execz .LBB0_1290
	s_waitcnt lgkmcnt(0)
	v_add_f32_e32 v32, v32, v33
	v_mul_f32_e32 v32, 0x4f800000, v32
	v_rndne_f32_e32 v32, v32
	v_mul_f32_e32 v33, 0x2f800000, v32
	v_floor_f32_e32 v33, v33
	v_fmac_f32_e32 v32, 0xcf800000, v33
	v_cvt_u32_f32_e32 v32, v32
	v_cvt_u32_f32_e32 v33, v33
	v_mov_b32_e32 v236, v32
	v_mov_b32_e32 v237, v33
.LBB0_1290:
	s_or_b64 exec, exec, s[14:15]
	v_add_u32_e32 v32, 0xa0, v146
	s_waitcnt lgkmcnt(0)
	v_ashrrev_i32_e32 v33, 31, v32
	s_waitcnt vmcnt(19)
	v_mov_b32_e32 v34, v220
	v_mov_b32_e32 v35, v221
	v_mov_b32_e32 v128, v35
	v_lshlrev_b64 v[36:37], s16, v[128:129]
	v_min_u32_e32 v35, 1, v36
	v_or_b32_e32 v35, v37, v35
	v_lshlrev_b64 v[36:37], 11, v[32:33]
	v_lshl_add_u64 v[36:37], v[36:37], 0, v[130:131]
	v_lshlrev_b64 v[48:49], 2, v[36:37]
	v_lshl_add_u64 v[38:39], s[8:9], 0, v[48:49]
	global_load_dwordx4 v[40:43], v[38:39], off offset:16 nt
	global_load_dwordx4 v[44:47], v[38:39], off nt
	global_load_dwordx4 v[166:169], v[38:39], off offset:528 nt
	global_load_dwordx4 v[170:173], v[38:39], off offset:512 nt
	v_cvt_f32_u32_e32 v35, v35
	v_cvt_f32_u32_e32 v34, v34
	v_ldexp_f32 v35, v35, s17
	v_fmac_f32_e32 v35, 0x2f800000, v34
	v_fmamk_f32 v34, v35, 0x3b000000, v195
	v_cmp_gt_f32_e32 vcc, s27, v34
	v_mul_f32_e32 v35, 0x4b800000, v34
	s_nop 0
	v_cndmask_b32_e32 v34, v34, v35, vcc
	v_rsq_f32_e32 v34, v34
	s_nop 0
	v_mul_f32_e32 v35, 0x45800000, v34
	v_cndmask_b32_e32 v34, v34, v35, vcc
	s_waitcnt vmcnt(3)
	v_pk_fma_f32 v[28:29], v[28:29], v[34:35], v[40:41] op_sel_hi:[1,0,1]
	s_waitcnt vmcnt(2)
	v_pk_fma_f32 v[26:27], v[26:27], v[34:35], v[46:47] op_sel_hi:[1,0,1]
	v_pk_fma_f32 v[24:25], v[24:25], v[34:35], v[44:45] op_sel_hi:[1,0,1]
	v_lshl_add_u64 v[40:41], s[60:61], 0, v[48:49]
	v_pk_fma_f32 v[30:31], v[30:31], v[34:35], v[42:43] op_sel_hi:[1,0,1]
	global_store_dwordx4 v[40:41], v[24:27], off
	global_store_dwordx4 v[40:41], v[28:31], off offset:16
	v_cvt_pk_bf16_f32 v40, v24, v25
	v_mul_f32_e32 v25, v25, v25
	v_fmac_f32_e32 v25, v24, v24
	v_mul_f32_e32 v24, v27, v27
	v_fmac_f32_e32 v24, v26, v26
	v_add_f32_e32 v24, v25, v24
	v_mul_f32_e32 v25, v29, v29
	v_fmac_f32_e32 v25, v28, v28
	v_cvt_pk_bf16_f32 v41, v26, v27
	v_cvt_pk_bf16_f32 v42, v28, v29
	v_cvt_pk_bf16_f32 v43, v30, v31
	v_lshl_add_u64 v[44:45], v[36:37], 1, s[62:63]
	v_add_f32_e32 v24, v25, v24
	v_mul_f32_e32 v25, v31, v31
	global_store_dwordx4 v[44:45], v[40:43], off
	v_fmac_f32_e32 v25, v30, v30
	v_add_f32_e32 v35, v25, v24
	v_or_b32_e32 v36, 0x80, v36
	s_waitcnt vmcnt(3)
	v_mov_b32_e32 v24, v166
	v_mov_b32_e32 v25, v167
	v_mov_b32_e32 v26, v168
	v_mov_b32_e32 v27, v169
	v_mov_b32_e32 v28, v170
	v_mov_b32_e32 v29, v171
	v_mov_b32_e32 v30, v172
	v_mov_b32_e32 v31, v173
	v_pk_fma_f32 v[20:21], v[20:21], v[34:35], v[24:25] op_sel_hi:[1,0,1]
	v_pk_fma_f32 v[18:19], v[18:19], v[34:35], v[30:31] op_sel_hi:[1,0,1]
	v_pk_fma_f32 v[16:17], v[16:17], v[34:35], v[28:29] op_sel_hi:[1,0,1]
	v_lshl_add_u64 v[24:25], v[36:37], 2, s[60:61]
	v_pk_fma_f32 v[22:23], v[22:23], v[34:35], v[26:27] op_sel_hi:[1,0,1]
	global_store_dwordx4 v[24:25], v[16:19], off
	global_store_dwordx4 v[24:25], v[20:23], off offset:16
	v_cvt_pk_bf16_f32 v24, v16, v17
	v_mul_f32_e32 v17, v17, v17
	v_fmac_f32_e32 v17, v16, v16
	v_mul_f32_e32 v16, v19, v19
	v_fmac_f32_e32 v16, v18, v18
	v_add_f32_e32 v16, v17, v16
	v_mul_f32_e32 v17, v21, v21
	v_fmac_f32_e32 v17, v20, v20
	v_add_f32_e32 v16, v17, v16
	v_mul_f32_e32 v17, v23, v23
	v_fmac_f32_e32 v17, v22, v22
	v_add_f32_e32 v16, v17, v16
	v_add_f32_e32 v16, v35, v16
	ds_bpermute_b32 v17, v115, v16
	v_cvt_pk_bf16_f32 v25, v18, v19
	v_cvt_pk_bf16_f32 v26, v20, v21
	v_cvt_pk_bf16_f32 v27, v22, v23
	v_lshl_add_u64 v[28:29], v[36:37], 1, s[62:63]
	s_waitcnt lgkmcnt(0)
	v_add_f32_e32 v16, v16, v17
	ds_bpermute_b32 v17, v120, v16
	global_store_dwordx4 v[28:29], v[24:27], off
	s_and_saveexec_b64 s[14:15], s[48:49]
	s_cbranch_execz .LBB0_1292
	s_waitcnt lgkmcnt(0)
	v_add_f32_e32 v16, v16, v17
	v_mul_f32_e32 v16, 0x4f800000, v16
	v_rndne_f32_e32 v16, v16
	v_mul_f32_e32 v17, 0x2f800000, v16
	v_floor_f32_e32 v17, v17
	v_fmac_f32_e32 v16, 0xcf800000, v17
	v_cvt_u32_f32_e32 v16, v16
	v_cvt_u32_f32_e32 v17, v17
	v_mov_b32_e32 v238, v16
	v_mov_b32_e32 v239, v17
; DI void ss_add(ssacc_t* p, float v) { atomicAdd(p, (ssacc_t)__float2ull_rn(v * 4294967296.f)); }
; DI float ss_get(const ssacc_t* p) { const ssacc_t v = *p; return (float)(unsigned)(v >> 32) + (float)(unsigned)(v & 0xffffffffull) * 2.3283064365386963e-10f; }
; DI float quad_sum(float s) { s += __shfl_xor(s, 16); s += __shfl_xor(s, 32); return s; }
; DI float sq8(const f32x4& a, const f32x4& b) { return (a[0] * a[0] + a[1] * a[1]) + (a[2] * a[2] + a[3] * a[3]) + (b[0] * b[0] + b[1] * b[1]) + (b[2] * b[2] + b[3] * b[3]); }
; DI u32x4 pack8(const f32x4& a, const f32x4& b) { u32x4 w; w.x = cvtpk(a[0], a[1]); w.y = cvtpk(a[2], a[3]); w.z = cvtpk(b[0], b[1]); w.w = cvtpk(b[2], b[3]); return w; }
;     DI void operator()(const Acc& acc, const Unit& u, int wr, int wc, int fr, int fq) const {
;     ...
;             for (int m = 0; m < 4; ++m) {
;                 asm volatile("" ::: "memory");
;                 const int row = u.pm * 256 + ai * 128 + wr * 64 + m * 16 + fr;
;                 const float rs = rsqrtf(ss_get(ss_dil + row) * (1.f / 512.f) + EPS_);
;                 float sq = 0.f;
; #pragma unroll
;                 for (int bj = 0; bj < 2; ++bj) {
;                     const size_t off = (size_t)row * 2048 + u.pn * 256 + bj * 128 + wc * 32 + 8 * fq;
;                     const f32x4 v0 = *(const f32x4*)(xin + off) + acc[ai][bj][m][0] * rs, v1 = *(const f32x4*)(xin + off + 4) + acc[ai][bj][m][1] * rs;
;                     *(f32x4*)(X + off) = v0; *(f32x4*)(X + off + 4) = v1; *(u32x4*)(XB + off) = pack8(v0, v1); sq += sq8(v0, v1);
;                 }
;                 sq = quad_sum(sq); if (fq == 0) ss_add(ssx1 + row, sq);
;             }
.LBB0_1292:
	s_or_b64 exec, exec, s[14:15]
	v_add_u32_e32 v16, 0xb0, v146
	s_waitcnt lgkmcnt(0)
	v_ashrrev_i32_e32 v17, 31, v16
	s_waitcnt vmcnt(21)
	v_mov_b32_e32 v18, v222
	v_mov_b32_e32 v19, v223
	v_mov_b32_e32 v128, v19
	v_lshlrev_b64 v[20:21], s16, v[128:129]
	v_min_u32_e32 v19, 1, v20
	v_or_b32_e32 v19, v21, v19
	v_lshlrev_b64 v[20:21], 11, v[16:17]
	v_lshl_add_u64 v[20:21], v[20:21], 0, v[130:131]
	v_lshlrev_b64 v[32:33], 2, v[20:21]
	v_lshl_add_u64 v[22:23], s[8:9], 0, v[32:33]
	global_load_dwordx4 v[24:27], v[22:23], off offset:16 nt
	global_load_dwordx4 v[28:31], v[22:23], off nt
	global_load_dwordx4 v[166:169], v[22:23], off offset:528 nt
	global_load_dwordx4 v[170:173], v[22:23], off offset:512 nt
	v_cvt_f32_u32_e32 v19, v19
	v_cvt_f32_u32_e32 v18, v18
	v_ldexp_f32 v19, v19, s17
	v_fmac_f32_e32 v19, 0x2f800000, v18
	v_fmamk_f32 v18, v19, 0x3b000000, v195
	v_cmp_gt_f32_e32 vcc, s27, v18
	v_mul_f32_e32 v19, 0x4b800000, v18
	s_nop 0
	v_cndmask_b32_e32 v18, v18, v19, vcc
	v_rsq_f32_e32 v18, v18
	s_nop 0
	v_mul_f32_e32 v19, 0x45800000, v18
	v_cndmask_b32_e32 v18, v18, v19, vcc
	s_waitcnt vmcnt(3)
	v_pk_fma_f32 v[12:13], v[12:13], v[18:19], v[24:25] op_sel_hi:[1,0,1]
	s_waitcnt vmcnt(2)
	v_pk_fma_f32 v[10:11], v[10:11], v[18:19], v[30:31] op_sel_hi:[1,0,1]
	v_pk_fma_f32 v[8:9], v[8:9], v[18:19], v[28:29] op_sel_hi:[1,0,1]
	v_lshl_add_u64 v[24:25], s[60:61], 0, v[32:33]
	v_pk_fma_f32 v[14:15], v[14:15], v[18:19], v[26:27] op_sel_hi:[1,0,1]
	global_store_dwordx4 v[24:25], v[8:11], off
	global_store_dwordx4 v[24:25], v[12:15], off offset:16
	v_cvt_pk_bf16_f32 v24, v8, v9
	v_mul_f32_e32 v9, v9, v9
	v_fmac_f32_e32 v9, v8, v8
	v_mul_f32_e32 v8, v11, v11
	v_fmac_f32_e32 v8, v10, v10
	v_add_f32_e32 v8, v9, v8
	v_mul_f32_e32 v9, v13, v13
	v_fmac_f32_e32 v9, v12, v12
	v_cvt_pk_bf16_f32 v25, v10, v11
	v_cvt_pk_bf16_f32 v26, v12, v13
	v_cvt_pk_bf16_f32 v27, v14, v15
	v_lshl_add_u64 v[28:29], v[20:21], 1, s[62:63]
	v_add_f32_e32 v8, v9, v8
	v_mul_f32_e32 v9, v15, v15
	global_store_dwordx4 v[28:29], v[24:27], off
	v_fmac_f32_e32 v9, v14, v14
	v_add_f32_e32 v19, v9, v8
	v_or_b32_e32 v20, 0x80, v20
	s_waitcnt vmcnt(3)
	v_mov_b32_e32 v8, v166
	v_mov_b32_e32 v9, v167
	v_mov_b32_e32 v10, v168
	v_mov_b32_e32 v11, v169
	v_mov_b32_e32 v12, v170
	v_mov_b32_e32 v13, v171
	v_mov_b32_e32 v14, v172
	v_mov_b32_e32 v15, v173
	v_pk_fma_f32 v[4:5], v[4:5], v[18:19], v[8:9] op_sel_hi:[1,0,1]
	v_pk_fma_f32 v[2:3], v[2:3], v[18:19], v[14:15] op_sel_hi:[1,0,1]
	v_pk_fma_f32 v[0:1], v[0:1], v[18:19], v[12:13] op_sel_hi:[1,0,1]
	v_lshl_add_u64 v[8:9], v[20:21], 2, s[60:61]
	v_pk_fma_f32 v[6:7], v[6:7], v[18:19], v[10:11] op_sel_hi:[1,0,1]
	global_store_dwordx4 v[8:9], v[0:3], off
	global_store_dwordx4 v[8:9], v[4:7], off offset:16
	v_cvt_pk_bf16_f32 v8, v0, v1
	v_mul_f32_e32 v1, v1, v1
	v_fmac_f32_e32 v1, v0, v0
	v_mul_f32_e32 v0, v3, v3
	v_fmac_f32_e32 v0, v2, v2
	v_add_f32_e32 v0, v1, v0
	v_mul_f32_e32 v1, v5, v5
	v_fmac_f32_e32 v1, v4, v4
	v_add_f32_e32 v0, v1, v0
	v_mul_f32_e32 v1, v7, v7
	v_fmac_f32_e32 v1, v6, v6
	v_add_f32_e32 v0, v1, v0
	v_add_f32_e32 v0, v19, v0
	ds_bpermute_b32 v1, v115, v0
	v_cvt_pk_bf16_f32 v9, v2, v3
	v_cvt_pk_bf16_f32 v10, v4, v5
	v_cvt_pk_bf16_f32 v11, v6, v7
	v_lshl_add_u64 v[12:13], v[20:21], 1, s[62:63]
	s_waitcnt lgkmcnt(0)
	v_add_f32_e32 v0, v0, v1
	ds_bpermute_b32 v1, v120, v0
	global_store_dwordx4 v[12:13], v[8:11], off
	s_and_saveexec_b64 s[14:15], s[48:49]
	s_cbranch_execz .LBB0_1294
	s_waitcnt lgkmcnt(0)
	v_add_f32_e32 v0, v0, v1
	v_mul_f32_e32 v0, 0x4f800000, v0
	v_rndne_f32_e32 v0, v0
	v_mul_f32_e32 v1, 0x2f800000, v0
	v_floor_f32_e32 v1, v1
	v_fmac_f32_e32 v0, 0xcf800000, v1
	v_cvt_u32_f32_e32 v0, v0
	v_cvt_u32_f32_e32 v1, v1
	v_lshl_add_u64 v[2:3], v[16:17], 3, s[58:59]
	global_atomic_add_x2 v[224:225], v[226:227], off
	global_atomic_add_x2 v[224:225], v[228:229], off offset:128
	global_atomic_add_x2 v[224:225], v[230:231], off offset:256
	global_atomic_add_x2 v[224:225], v[232:233], off offset:384
	global_atomic_add_x2 v[224:225], v[234:235], off offset:1024
	global_atomic_add_x2 v[224:225], v[236:237], off offset:1152
	global_atomic_add_x2 v[224:225], v[238:239], off offset:1280
	global_atomic_add_x2 v[2:3], v[0:1], off

; DI void ss_add(ssacc_t* p, float v) { atomicAdd(p, (ssacc_t)__float2ull_rn(v * 4294967296.f)); }
; DI float quad_sum(float s) { s += __shfl_xor(s, 16); s += __shfl_xor(s, 32); return s; }
; DI float sq8(const f32x4& a, const f32x4& b) { return (a[0] * a[0] + a[1] * a[1]) + (a[2] * a[2] + a[3] * a[3]) + (b[0] * b[0] + b[1] * b[1]) + (b[2] * b[2] + b[3] * b[3]); }
; DI u32x4 pack8(const f32x4& a, const f32x4& b) { u32x4 w; w.x = cvtpk(a[0], a[1]); w.y = cvtpk(a[2], a[3]); w.z = cvtpk(b[0], b[1]); w.w = cvtpk(b[2], b[3]); return w; }
;     DI void operator()(const Acc& acc, const Unit& u, int wr, int wc, int fr, int fq) const {
;     ...
;             for (int m = 0; m < 4; ++m) {
;                 asm volatile("" ::: "memory");
;                 const int row = u.pm * 256 + ai * 128 + wr * 64 + m * 16 + fr;
;                 float sq = 0.f;
; #pragma unroll
;                 for (int bj = 0; bj < 2; ++bj) {
;                     const size_t off = (size_t)row * 2048 + u.pn * 256 + bj * 128 + wc * 32 + 8 * fq;
;                     const f32x4 v0 = *(const f32x4*)(X + off) + acc[ai][bj][m][0], v1 = *(const f32x4*)(X + off + 4) + acc[ai][bj][m][1];
;                     *(f32x4*)(X + off) = v0; *(f32x4*)(X + off + 4) = v1; *(u32x4*)(XB + off) = pack8(v0, v1); sq += sq8(v0, v1);
;                 }
;                 sq = quad_sum(sq); if (fq == 0) ss_add(ssx + row, sq);
;             }
.LBB0_1567:
	v_lshl_add_u32 v144, s66, 8, v137
	s_lshl_b32 s4, s65, 8
	s_ashr_i32 s14, s4, 31
	v_ashrrev_i32_e32 v145, 31, v144
	v_mov_b32_e32 v143, s14
	v_or_b32_e32 v142, s4, v136
	v_lshlrev_b64 v[148:149], 11, v[144:145]
	v_lshl_add_u64 v[156:157], v[148:149], 0, v[142:143]
	v_lshl_add_u64 v[158:159], v[156:157], 2, s[44:45]
	v_mov_b32_e32 v190, v158
	v_mov_b32_e32 v191, v159
	global_load_dwordx4 v[160:163], v[158:159], off offset:16 nt
	global_load_dwordx4 v[164:167], v[158:159], off nt
	s_mov_b64 s[100:101], 0x200
	v_lshl_add_u64 v[192:193], v[190:191], 0, s[100:101]
	global_load_dwordx4 v[168:171], v[192:193], off offset:16 nt
	global_load_dwordx4 v[172:175], v[192:193], off nt
	s_mov_b64 s[100:101], 0x20000
	v_lshl_add_u64 v[192:193], v[190:191], 0, s[100:101]
	global_load_dwordx4 v[176:179], v[192:193], off offset:16 nt
	global_load_dwordx4 v[180:183], v[192:193], off nt
	s_mov_b64 s[100:101], 0x20200
	v_lshl_add_u64 v[192:193], v[190:191], 0, s[100:101]
	global_load_dwordx4 v[208:211], v[192:193], off offset:16 nt
	global_load_dwordx4 v[212:215], v[192:193], off nt
	s_mov_b64 s[100:101], 0x40000
	v_lshl_add_u64 v[192:193], v[190:191], 0, s[100:101]
	global_load_dwordx4 v[216:219], v[192:193], off offset:16 nt
	global_load_dwordx4 v[220:223], v[192:193], off nt
	s_mov_b64 s[100:101], 0x40200
	v_lshl_add_u64 v[192:193], v[190:191], 0, s[100:101]
	global_load_dwordx4 v[224:227], v[192:193], off offset:16 nt
	global_load_dwordx4 v[228:231], v[192:193], off nt
	s_waitcnt vmcnt(10)
	v_mov_b32_e32 v148, v160
	v_mov_b32_e32 v149, v161
	v_mov_b32_e32 v150, v162
	v_mov_b32_e32 v151, v163
	v_mov_b32_e32 v152, v164
	v_mov_b32_e32 v153, v165
	v_mov_b32_e32 v154, v166
	v_mov_b32_e32 v155, v167
	s_mov_b64 s[100:101], 0x60000
	v_lshl_add_u64 v[192:193], v[190:191], 0, s[100:101]
	global_load_dwordx4 v[160:163], v[192:193], off offset:16 nt
	global_load_dwordx4 v[164:167], v[192:193], off nt
	v_pk_add_f32 v[126:127], v[126:127], v[150:151]
	v_pk_add_f32 v[122:123], v[122:123], v[154:155]
	v_pk_add_f32 v[120:121], v[120:121], v[152:153]
	v_pk_add_f32 v[124:125], v[124:125], v[148:149]
	global_store_dwordx4 v[158:159], v[120:123], off
	global_store_dwordx4 v[158:159], v[124:127], off offset:16
	v_cvt_pk_bf16_f32 v148, v120, v121
	v_mul_f32_e32 v121, v121, v121
	v_fmac_f32_e32 v121, v120, v120
	v_mul_f32_e32 v120, v123, v123
	v_fmac_f32_e32 v120, v122, v122
	v_add_f32_e32 v120, v121, v120
	v_mul_f32_e32 v121, v125, v125
	v_fmac_f32_e32 v121, v124, v124
	v_cvt_pk_bf16_f32 v149, v122, v123
	v_cvt_pk_bf16_f32 v150, v124, v125
	v_cvt_pk_bf16_f32 v151, v126, v127
	v_lshl_add_u64 v[152:153], v[156:157], 1, s[50:51]
	v_add_f32_e32 v120, v120, v121
	v_mul_f32_e32 v121, v127, v127
	v_or_b32_e32 v156, 0x80, v156
	global_store_dwordx4 v[152:153], v[148:151], off
	v_fmac_f32_e32 v121, v126, v126
	s_nop 0
	v_lshl_add_u64 v[148:149], v[156:157], 2, s[44:45]
	v_add_f32_e32 v150, v121, v120
	s_waitcnt vmcnt(13)
	v_mov_b32_e32 v120, v168
	v_mov_b32_e32 v121, v169
	v_mov_b32_e32 v122, v170
	v_mov_b32_e32 v123, v171
	v_mov_b32_e32 v124, v172
	v_mov_b32_e32 v125, v173
	v_mov_b32_e32 v126, v174
	v_mov_b32_e32 v127, v175
	s_mov_b64 s[100:101], 0x60200
	v_lshl_add_u64 v[192:193], v[190:191], 0, s[100:101]
	global_load_dwordx4 v[168:171], v[192:193], off offset:16 nt
	global_load_dwordx4 v[172:175], v[192:193], off nt
	v_pk_add_f32 v[114:115], v[114:115], v[122:123]
	v_pk_add_f32 v[118:119], v[118:119], v[126:127]
	v_pk_add_f32 v[116:117], v[116:117], v[124:125]
	v_pk_add_f32 v[112:113], v[112:113], v[120:121]
	global_store_dwordx4 v[148:149], v[116:119], off
	global_store_dwordx4 v[148:149], v[112:115], off offset:16
	v_cvt_pk_bf16_f32 v120, v116, v117
	v_mul_f32_e32 v117, v117, v117
	v_fmac_f32_e32 v117, v116, v116
	v_mul_f32_e32 v116, v119, v119
	v_cvt_pk_bf16_f32 v122, v112, v113
	v_fmac_f32_e32 v116, v118, v118
	v_mul_f32_e32 v113, v113, v113
	v_add_f32_e32 v116, v117, v116
	v_fmac_f32_e32 v113, v112, v112
	v_add_f32_e32 v112, v116, v113
	v_mul_f32_e32 v113, v115, v115
	v_cvt_pk_bf16_f32 v123, v114, v115
	v_fmac_f32_e32 v113, v114, v114
	v_and_b32_e32 v114, 64, v199
	v_add_f32_e32 v112, v113, v112
	v_xor_b32_e32 v113, 16, v199
	v_add_u32_e32 v115, 64, v114
	v_cmp_lt_i32_e32 vcc, v113, v115
	v_add_f32_e32 v112, v150, v112
	v_cvt_pk_bf16_f32 v121, v118, v119
	v_cndmask_b32_e32 v113, v199, v113, vcc
	v_lshlrev_b32_e32 v116, 2, v113
	ds_bpermute_b32 v113, v116, v112
	v_lshl_add_u64 v[124:125], v[156:157], 1, s[50:51]
	global_store_dwordx4 v[124:125], v[120:123], off
	s_waitcnt lgkmcnt(0)
	v_add_f32_e32 v114, v112, v113
	v_xor_b32_e32 v112, 32, v199
	v_cmp_lt_i32_e32 vcc, v112, v115
	s_nop 1
	v_cndmask_b32_e32 v112, v199, v112, vcc
	v_lshlrev_b32_e32 v117, 2, v112
	ds_bpermute_b32 v115, v117, v114
	v_lshl_add_u64 v[112:113], v[144:145], 3, s[52:53]
	s_and_saveexec_b64 s[14:15], s[46:47]
	s_cbranch_execz .LBB0_1569
	s_waitcnt lgkmcnt(0)
	v_add_f32_e32 v114, v114, v115
	v_mul_f32_e32 v114, 0x4f800000, v114
	v_rndne_f32_e32 v114, v114
	v_mul_f32_e32 v115, 0x2f800000, v114
	v_floor_f32_e32 v115, v115
	v_fmac_f32_e32 v114, 0xcf800000, v115
	v_cvt_u32_f32_e32 v114, v114
	v_cvt_u32_f32_e32 v115, v115
	v_mov_b32_e32 v232, v114
	v_mov_b32_e32 v233, v115
; DI void ss_add(ssacc_t* p, float v) { atomicAdd(p, (ssacc_t)__float2ull_rn(v * 4294967296.f)); }
; DI float quad_sum(float s) { s += __shfl_xor(s, 16); s += __shfl_xor(s, 32); return s; }
; DI float sq8(const f32x4& a, const f32x4& b) { return (a[0] * a[0] + a[1] * a[1]) + (a[2] * a[2] + a[3] * a[3]) + (b[0] * b[0] + b[1] * b[1]) + (b[2] * b[2] + b[3] * b[3]); }
; DI u32x4 pack8(const f32x4& a, const f32x4& b) { u32x4 w; w.x = cvtpk(a[0], a[1]); w.y = cvtpk(a[2], a[3]); w.z = cvtpk(b[0], b[1]); w.w = cvtpk(b[2], b[3]); return w; }
;     DI void operator()(const Acc& acc, const Unit& u, int wr, int wc, int fr, int fq) const {
;     ...
;             for (int m = 0; m < 4; ++m) {
;                 asm volatile("" ::: "memory");
;                 const int row = u.pm * 256 + ai * 128 + wr * 64 + m * 16 + fr;
;                 float sq = 0.f;
; #pragma unroll
;                 for (int bj = 0; bj < 2; ++bj) {
;                     const size_t off = (size_t)row * 2048 + u.pn * 256 + bj * 128 + wc * 32 + 8 * fq;
;                     const f32x4 v0 = *(const f32x4*)(X + off) + acc[ai][bj][m][0], v1 = *(const f32x4*)(X + off + 4) + acc[ai][bj][m][1];
;                     *(f32x4*)(X + off) = v0; *(f32x4*)(X + off + 4) = v1; *(u32x4*)(XB + off) = pack8(v0, v1); sq += sq8(v0, v1);
;                 }
;                 sq = quad_sum(sq); if (fq == 0) ss_add(ssx + row, sq);
;             }
.LBB0_1569:
	s_or_b64 exec, exec, s[14:15]
	v_or_b32_e32 v114, 16, v144
	s_waitcnt lgkmcnt(0)
	v_ashrrev_i32_e32 v115, 31, v114
	v_lshlrev_b64 v[114:115], 11, v[114:115]
	v_lshl_add_u64 v[114:115], v[114:115], 0, v[142:143]
	v_lshl_add_u64 v[126:127], v[114:115], 2, s[44:45]
	s_waitcnt vmcnt(16)
	v_mov_b32_e32 v118, v176
	v_mov_b32_e32 v119, v177
	v_mov_b32_e32 v120, v178
	v_mov_b32_e32 v121, v179
	v_mov_b32_e32 v122, v180
	v_mov_b32_e32 v123, v181
	v_mov_b32_e32 v124, v182
	v_mov_b32_e32 v125, v183
	s_mov_b64 s[100:101], 0x100000
	v_lshl_add_u64 v[192:193], v[190:191], 0, s[100:101]
	global_load_dwordx4 v[176:179], v[192:193], off offset:16 nt
	global_load_dwordx4 v[180:183], v[192:193], off nt
	v_pk_add_f32 v[106:107], v[106:107], v[120:121]
	v_pk_add_f32 v[110:111], v[110:111], v[124:125]
	v_pk_add_f32 v[108:109], v[108:109], v[122:123]
	v_pk_add_f32 v[104:105], v[104:105], v[118:119]
	global_store_dwordx4 v[126:127], v[108:111], off
	global_store_dwordx4 v[126:127], v[104:107], off offset:16
	v_cvt_pk_bf16_f32 v118, v108, v109
	v_mul_f32_e32 v109, v109, v109
	v_fmac_f32_e32 v109, v108, v108
	v_mul_f32_e32 v108, v111, v111
	v_cvt_pk_bf16_f32 v120, v104, v105
	v_fmac_f32_e32 v108, v110, v110
	v_mul_f32_e32 v105, v105, v105
	v_add_f32_e32 v108, v109, v108
	v_fmac_f32_e32 v105, v104, v104
	v_cvt_pk_bf16_f32 v119, v110, v111
	v_cvt_pk_bf16_f32 v121, v106, v107
	v_lshl_add_u64 v[122:123], v[114:115], 1, s[50:51]
	v_add_f32_e32 v104, v108, v105
	v_mul_f32_e32 v105, v107, v107
	v_or_b32_e32 v114, 0x80, v114
	global_store_dwordx4 v[122:123], v[118:121], off
	v_fmac_f32_e32 v105, v106, v106
	s_nop 0
	v_lshl_add_u64 v[118:119], v[114:115], 2, s[44:45]
	v_add_f32_e32 v120, v105, v104
	s_waitcnt vmcnt(19)
	v_mov_b32_e32 v104, v208
	v_mov_b32_e32 v105, v209
	v_mov_b32_e32 v106, v210
	v_mov_b32_e32 v107, v211
	v_mov_b32_e32 v108, v212
	v_mov_b32_e32 v109, v213
	v_mov_b32_e32 v110, v214
	v_mov_b32_e32 v111, v215
	s_mov_b64 s[100:101], 0x100200
	v_lshl_add_u64 v[192:193], v[190:191], 0, s[100:101]
	global_load_dwordx4 v[208:211], v[192:193], off offset:16 nt
	global_load_dwordx4 v[212:215], v[192:193], off nt
	v_pk_add_f32 v[98:99], v[98:99], v[106:107]
	v_pk_add_f32 v[102:103], v[102:103], v[110:111]
	v_pk_add_f32 v[100:101], v[100:101], v[108:109]
	v_pk_add_f32 v[96:97], v[96:97], v[104:105]
	global_store_dwordx4 v[118:119], v[100:103], off
	global_store_dwordx4 v[118:119], v[96:99], off offset:16
	v_cvt_pk_bf16_f32 v104, v100, v101
	v_mul_f32_e32 v101, v101, v101
	v_fmac_f32_e32 v101, v100, v100
	v_mul_f32_e32 v100, v103, v103
	v_cvt_pk_bf16_f32 v106, v96, v97
	v_fmac_f32_e32 v100, v102, v102
	v_mul_f32_e32 v97, v97, v97
	v_add_f32_e32 v100, v101, v100
	v_fmac_f32_e32 v97, v96, v96
	v_add_f32_e32 v96, v100, v97
	v_mul_f32_e32 v97, v99, v99
	v_fmac_f32_e32 v97, v98, v98
	v_add_f32_e32 v96, v97, v96
	v_add_f32_e32 v96, v120, v96
	ds_bpermute_b32 v97, v116, v96
	v_cvt_pk_bf16_f32 v105, v102, v103
	v_cvt_pk_bf16_f32 v107, v98, v99
	v_lshl_add_u64 v[108:109], v[114:115], 1, s[50:51]
	global_store_dwordx4 v[108:109], v[104:107], off
	s_waitcnt lgkmcnt(0)
	v_add_f32_e32 v96, v96, v97
	ds_bpermute_b32 v97, v117, v96
	s_and_saveexec_b64 s[14:15], s[46:47]
	s_cbranch_execz .LBB0_1571
	s_waitcnt lgkmcnt(0)
	v_add_f32_e32 v96, v96, v97
	v_mul_f32_e32 v96, 0x4f800000, v96
	v_rndne_f32_e32 v96, v96
	v_mul_f32_e32 v97, 0x2f800000, v96
	v_floor_f32_e32 v97, v97
	v_fmac_f32_e32 v96, 0xcf800000, v97
	v_cvt_u32_f32_e32 v96, v96
	v_cvt_u32_f32_e32 v97, v97
	v_mov_b32_e32 v234, v96
	v_mov_b32_e32 v235, v97
.LBB0_1571:
	s_or_b64 exec, exec, s[14:15]
	v_or_b32_e32 v96, 32, v144
	s_waitcnt lgkmcnt(0)
	v_ashrrev_i32_e32 v97, 31, v96
	v_lshlrev_b64 v[96:97], 11, v[96:97]
	v_lshl_add_u64 v[96:97], v[96:97], 0, v[142:143]
	v_lshl_add_u64 v[106:107], v[96:97], 2, s[44:45]
	s_waitcnt vmcnt(22)
	v_mov_b32_e32 v98, v216
	v_mov_b32_e32 v99, v217
	v_mov_b32_e32 v100, v218
	v_mov_b32_e32 v101, v219
	v_mov_b32_e32 v102, v220
	v_mov_b32_e32 v103, v221
	v_mov_b32_e32 v104, v222
	v_mov_b32_e32 v105, v223
	s_mov_b64 s[100:101], 0x120000
	v_lshl_add_u64 v[192:193], v[190:191], 0, s[100:101]
	global_load_dwordx4 v[216:219], v[192:193], off offset:16 nt
	global_load_dwordx4 v[220:223], v[192:193], off nt
	v_pk_add_f32 v[90:91], v[90:91], v[100:101]
	v_pk_add_f32 v[94:95], v[94:95], v[104:105]
	v_pk_add_f32 v[92:93], v[92:93], v[102:103]
	v_pk_add_f32 v[88:89], v[88:89], v[98:99]
	global_store_dwordx4 v[106:107], v[92:95], off
	global_store_dwordx4 v[106:107], v[88:91], off offset:16
	v_cvt_pk_bf16_f32 v98, v92, v93
	v_mul_f32_e32 v93, v93, v93
	v_fmac_f32_e32 v93, v92, v92
	v_mul_f32_e32 v92, v95, v95
	v_cvt_pk_bf16_f32 v100, v88, v89
	v_fmac_f32_e32 v92, v94, v94
	v_mul_f32_e32 v89, v89, v89
	v_add_f32_e32 v92, v93, v92
	v_fmac_f32_e32 v89, v88, v88
	v_cvt_pk_bf16_f32 v99, v94, v95
	v_cvt_pk_bf16_f32 v101, v90, v91
	v_lshl_add_u64 v[102:103], v[96:97], 1, s[50:51]
	v_add_f32_e32 v88, v92, v89
	v_mul_f32_e32 v89, v91, v91
	v_or_b32_e32 v96, 0x80, v96
	global_store_dwordx4 v[102:103], v[98:101], off
	v_fmac_f32_e32 v89, v90, v90
	s_nop 0
	v_lshl_add_u64 v[98:99], v[96:97], 2, s[44:45]
	v_add_f32_e32 v100, v89, v88
	s_waitcnt vmcnt(25)
	v_mov_b32_e32 v88, v224
	v_mov_b32_e32 v89, v225
	v_mov_b32_e32 v90, v226
	v_mov_b32_e32 v91, v227
	v_mov_b32_e32 v92, v228
	v_mov_b32_e32 v93, v229
	v_mov_b32_e32 v94, v230
	v_mov_b32_e32 v95, v231
	s_mov_b64 s[100:101], 0x120200
	v_lshl_add_u64 v[192:193], v[190:191], 0, s[100:101]
	global_load_dwordx4 v[224:227], v[192:193], off offset:16 nt
	global_load_dwordx4 v[228:231], v[192:193], off nt
	v_pk_add_f32 v[82:83], v[82:83], v[90:91]
	v_pk_add_f32 v[86:87], v[86:87], v[94:95]
	v_pk_add_f32 v[84:85], v[84:85], v[92:93]
	v_pk_add_f32 v[80:81], v[80:81], v[88:89]
	global_store_dwordx4 v[98:99], v[84:87], off
	global_store_dwordx4 v[98:99], v[80:83], off offset:16
	v_cvt_pk_bf16_f32 v88, v84, v85
	v_mul_f32_e32 v85, v85, v85
	v_fmac_f32_e32 v85, v84, v84
	v_mul_f32_e32 v84, v87, v87
	v_cvt_pk_bf16_f32 v90, v80, v81
	v_fmac_f32_e32 v84, v86, v86
	v_mul_f32_e32 v81, v81, v81
	v_add_f32_e32 v84, v85, v84
	v_fmac_f32_e32 v81, v80, v80
	v_add_f32_e32 v80, v84, v81
	v_mul_f32_e32 v81, v83, v83
	v_fmac_f32_e32 v81, v82, v82
	v_add_f32_e32 v80, v81, v80
	v_add_f32_e32 v80, v100, v80
	ds_bpermute_b32 v81, v116, v80
	v_cvt_pk_bf16_f32 v89, v86, v87
	v_cvt_pk_bf16_f32 v91, v82, v83
	v_lshl_add_u64 v[92:93], v[96:97], 1, s[50:51]
	global_store_dwordx4 v[92:93], v[88:91], off
	s_waitcnt lgkmcnt(0)
	v_add_f32_e32 v80, v80, v81
	ds_bpermute_b32 v81, v117, v80
	s_and_saveexec_b64 s[14:15], s[46:47]
	s_cbranch_execz .LBB0_1573
	s_waitcnt lgkmcnt(0)
	v_add_f32_e32 v80, v80, v81
	v_mul_f32_e32 v80, 0x4f800000, v80
	v_rndne_f32_e32 v80, v80
	v_mul_f32_e32 v81, 0x2f800000, v80
	v_floor_f32_e32 v81, v81
	v_fmac_f32_e32 v80, 0xcf800000, v81
	v_cvt_u32_f32_e32 v80, v80
	v_cvt_u32_f32_e32 v81, v81
	v_mov_b32_e32 v236, v80
	v_mov_b32_e32 v237, v81
; DI void ss_add(ssacc_t* p, float v) { atomicAdd(p, (ssacc_t)__float2ull_rn(v * 4294967296.f)); }
; DI float quad_sum(float s) { s += __shfl_xor(s, 16); s += __shfl_xor(s, 32); return s; }
; DI float sq8(const f32x4& a, const f32x4& b) { return (a[0] * a[0] + a[1] * a[1]) + (a[2] * a[2] + a[3] * a[3]) + (b[0] * b[0] + b[1] * b[1]) + (b[2] * b[2] + b[3] * b[3]); }
; DI u32x4 pack8(const f32x4& a, const f32x4& b) { u32x4 w; w.x = cvtpk(a[0], a[1]); w.y = cvtpk(a[2], a[3]); w.z = cvtpk(b[0], b[1]); w.w = cvtpk(b[2], b[3]); return w; }
;     DI void operator()(const Acc& acc, const Unit& u, int wr, int wc, int fr, int fq) const {
;     ...
;             for (int m = 0; m < 4; ++m) {
;                 asm volatile("" ::: "memory");
;                 const int row = u.pm * 256 + ai * 128 + wr * 64 + m * 16 + fr;
;                 float sq = 0.f;
; #pragma unroll
;                 for (int bj = 0; bj < 2; ++bj) {
;                     const size_t off = (size_t)row * 2048 + u.pn * 256 + bj * 128 + wc * 32 + 8 * fq;
;                     const f32x4 v0 = *(const f32x4*)(X + off) + acc[ai][bj][m][0], v1 = *(const f32x4*)(X + off + 4) + acc[ai][bj][m][1];
;                     *(f32x4*)(X + off) = v0; *(f32x4*)(X + off + 4) = v1; *(u32x4*)(XB + off) = pack8(v0, v1); sq += sq8(v0, v1);
;                 }
;                 sq = quad_sum(sq); if (fq == 0) ss_add(ssx + row, sq);
;             }
.LBB0_1573:
	s_or_b64 exec, exec, s[14:15]
	v_or_b32_e32 v80, 48, v144
	s_waitcnt lgkmcnt(0)
	v_ashrrev_i32_e32 v81, 31, v80
	v_lshlrev_b64 v[80:81], 11, v[80:81]
	v_lshl_add_u64 v[80:81], v[80:81], 0, v[142:143]
	v_lshl_add_u64 v[90:91], v[80:81], 2, s[44:45]
	s_waitcnt vmcnt(28)
	v_mov_b32_e32 v82, v160
	v_mov_b32_e32 v83, v161
	v_mov_b32_e32 v84, v162
	v_mov_b32_e32 v85, v163
	v_mov_b32_e32 v86, v164
	v_mov_b32_e32 v87, v165
	v_mov_b32_e32 v88, v166
	v_mov_b32_e32 v89, v167
	s_mov_b64 s[100:101], 0x140000
	v_lshl_add_u64 v[192:193], v[190:191], 0, s[100:101]
	global_load_dwordx4 v[160:163], v[192:193], off offset:16 nt
	global_load_dwordx4 v[164:167], v[192:193], off nt
	v_pk_add_f32 v[74:75], v[74:75], v[84:85]
	v_pk_add_f32 v[78:79], v[78:79], v[88:89]
	v_pk_add_f32 v[76:77], v[76:77], v[86:87]
	v_pk_add_f32 v[72:73], v[72:73], v[82:83]
	global_store_dwordx4 v[90:91], v[76:79], off
	global_store_dwordx4 v[90:91], v[72:75], off offset:16
	v_cvt_pk_bf16_f32 v82, v76, v77
	v_mul_f32_e32 v77, v77, v77
	v_fmac_f32_e32 v77, v76, v76
	v_mul_f32_e32 v76, v79, v79
	v_cvt_pk_bf16_f32 v84, v72, v73
	v_fmac_f32_e32 v76, v78, v78
	v_mul_f32_e32 v73, v73, v73
	v_add_f32_e32 v76, v77, v76
	v_fmac_f32_e32 v73, v72, v72
	v_cvt_pk_bf16_f32 v83, v78, v79
	v_cvt_pk_bf16_f32 v85, v74, v75
	v_lshl_add_u64 v[86:87], v[80:81], 1, s[50:51]
	v_add_f32_e32 v72, v76, v73
	v_mul_f32_e32 v73, v75, v75
	v_or_b32_e32 v80, 0x80, v80
	global_store_dwordx4 v[86:87], v[82:85], off
	v_fmac_f32_e32 v73, v74, v74
	s_nop 0
	v_lshl_add_u64 v[82:83], v[80:81], 2, s[44:45]
	v_add_f32_e32 v84, v73, v72
	s_waitcnt vmcnt(28)
	v_mov_b32_e32 v72, v168
	v_mov_b32_e32 v73, v169
	v_mov_b32_e32 v74, v170
	v_mov_b32_e32 v75, v171
	v_mov_b32_e32 v76, v172
	v_mov_b32_e32 v77, v173
	v_mov_b32_e32 v78, v174
	v_mov_b32_e32 v79, v175
	s_mov_b64 s[100:101], 0x140200
	v_lshl_add_u64 v[192:193], v[190:191], 0, s[100:101]
	global_load_dwordx4 v[168:171], v[192:193], off offset:16 nt
	global_load_dwordx4 v[172:175], v[192:193], off nt
	v_pk_add_f32 v[66:67], v[66:67], v[74:75]
	v_pk_add_f32 v[70:71], v[70:71], v[78:79]
	v_pk_add_f32 v[68:69], v[68:69], v[76:77]
	v_pk_add_f32 v[64:65], v[64:65], v[72:73]
	global_store_dwordx4 v[82:83], v[68:71], off
	global_store_dwordx4 v[82:83], v[64:67], off offset:16
	v_cvt_pk_bf16_f32 v72, v68, v69
	v_mul_f32_e32 v69, v69, v69
	v_fmac_f32_e32 v69, v68, v68
	v_mul_f32_e32 v68, v71, v71
	v_cvt_pk_bf16_f32 v74, v64, v65
	v_fmac_f32_e32 v68, v70, v70
	v_mul_f32_e32 v65, v65, v65
	v_add_f32_e32 v68, v69, v68
	v_fmac_f32_e32 v65, v64, v64
	v_add_f32_e32 v64, v68, v65
	v_mul_f32_e32 v65, v67, v67
	v_fmac_f32_e32 v65, v66, v66
	v_add_f32_e32 v64, v65, v64
	v_add_f32_e32 v64, v84, v64
	ds_bpermute_b32 v65, v116, v64
	v_cvt_pk_bf16_f32 v73, v70, v71
	v_cvt_pk_bf16_f32 v75, v66, v67
	v_lshl_add_u64 v[76:77], v[80:81], 1, s[50:51]
	global_store_dwordx4 v[76:77], v[72:75], off
	s_waitcnt lgkmcnt(0)
	v_add_f32_e32 v64, v64, v65
	ds_bpermute_b32 v65, v117, v64
	s_and_saveexec_b64 s[14:15], s[46:47]
	s_cbranch_execz .LBB0_1575
	s_waitcnt lgkmcnt(0)
	v_add_f32_e32 v64, v64, v65
	v_mul_f32_e32 v64, 0x4f800000, v64
	v_rndne_f32_e32 v64, v64
	v_mul_f32_e32 v65, 0x2f800000, v64
	v_floor_f32_e32 v65, v65
	v_fmac_f32_e32 v64, 0xcf800000, v65
	v_cvt_u32_f32_e32 v64, v64
	v_cvt_u32_f32_e32 v65, v65
	v_mov_b32_e32 v238, v64
	v_mov_b32_e32 v239, v65
.LBB0_1575:
	s_or_b64 exec, exec, s[14:15]
	v_add_u32_e32 v64, 0x80, v144
	s_waitcnt lgkmcnt(0)
	v_ashrrev_i32_e32 v65, 31, v64
	v_lshlrev_b64 v[64:65], 11, v[64:65]
	v_lshl_add_u64 v[64:65], v[64:65], 0, v[142:143]
	v_lshl_add_u64 v[74:75], v[64:65], 2, s[44:45]
	s_waitcnt vmcnt(28)
	v_mov_b32_e32 v66, v176
	v_mov_b32_e32 v67, v177
	v_mov_b32_e32 v68, v178
	v_mov_b32_e32 v69, v179
	v_mov_b32_e32 v70, v180
	v_mov_b32_e32 v71, v181
	v_mov_b32_e32 v72, v182
	v_mov_b32_e32 v73, v183
	s_mov_b64 s[100:101], 0x160000
	v_lshl_add_u64 v[192:193], v[190:191], 0, s[100:101]
	global_load_dwordx4 v[176:179], v[192:193], off offset:16 nt
	global_load_dwordx4 v[180:183], v[192:193], off nt
	v_pk_add_f32 v[58:59], v[58:59], v[68:69]
	v_pk_add_f32 v[62:63], v[62:63], v[72:73]
	v_pk_add_f32 v[60:61], v[60:61], v[70:71]
	v_pk_add_f32 v[56:57], v[56:57], v[66:67]
	global_store_dwordx4 v[74:75], v[60:63], off
	global_store_dwordx4 v[74:75], v[56:59], off offset:16
	v_cvt_pk_bf16_f32 v66, v60, v61
	v_mul_f32_e32 v61, v61, v61
	v_fmac_f32_e32 v61, v60, v60
	v_mul_f32_e32 v60, v63, v63
	v_cvt_pk_bf16_f32 v68, v56, v57
	v_fmac_f32_e32 v60, v62, v62
	v_mul_f32_e32 v57, v57, v57
	v_add_f32_e32 v60, v61, v60
	v_fmac_f32_e32 v57, v56, v56
	v_cvt_pk_bf16_f32 v67, v62, v63
	v_cvt_pk_bf16_f32 v69, v58, v59
	v_lshl_add_u64 v[70:71], v[64:65], 1, s[50:51]
	v_add_f32_e32 v56, v60, v57
	v_mul_f32_e32 v57, v59, v59
	v_or_b32_e32 v64, 0x80, v64
	global_store_dwordx4 v[70:71], v[66:69], off
	v_fmac_f32_e32 v57, v58, v58
	s_nop 0
	v_lshl_add_u64 v[66:67], v[64:65], 2, s[44:45]
	v_add_f32_e32 v68, v57, v56
	s_waitcnt vmcnt(28)
	v_mov_b32_e32 v56, v208
	v_mov_b32_e32 v57, v209
	v_mov_b32_e32 v58, v210
	v_mov_b32_e32 v59, v211
	v_mov_b32_e32 v60, v212
	v_mov_b32_e32 v61, v213
	v_mov_b32_e32 v62, v214
	v_mov_b32_e32 v63, v215
	s_mov_b64 s[100:101], 0x160200
	v_lshl_add_u64 v[192:193], v[190:191], 0, s[100:101]
	global_load_dwordx4 v[208:211], v[192:193], off offset:16 nt
	global_load_dwordx4 v[212:215], v[192:193], off nt
	v_pk_add_f32 v[50:51], v[50:51], v[58:59]
	v_pk_add_f32 v[54:55], v[54:55], v[62:63]
	v_pk_add_f32 v[52:53], v[52:53], v[60:61]
	v_pk_add_f32 v[48:49], v[48:49], v[56:57]
	global_store_dwordx4 v[66:67], v[52:55], off
	global_store_dwordx4 v[66:67], v[48:51], off offset:16
	v_cvt_pk_bf16_f32 v56, v52, v53
	v_mul_f32_e32 v53, v53, v53
	v_fmac_f32_e32 v53, v52, v52
	v_mul_f32_e32 v52, v55, v55
	v_cvt_pk_bf16_f32 v58, v48, v49
	v_fmac_f32_e32 v52, v54, v54
	v_mul_f32_e32 v49, v49, v49
	v_add_f32_e32 v52, v53, v52
	v_fmac_f32_e32 v49, v48, v48
	v_add_f32_e32 v48, v52, v49
	v_mul_f32_e32 v49, v51, v51
	v_fmac_f32_e32 v49, v50, v50
	v_add_f32_e32 v48, v49, v48
	v_add_f32_e32 v48, v68, v48
	ds_bpermute_b32 v49, v116, v48
	v_cvt_pk_bf16_f32 v57, v54, v55
	v_cvt_pk_bf16_f32 v59, v50, v51
	v_lshl_add_u64 v[60:61], v[64:65], 1, s[50:51]
	global_store_dwordx4 v[60:61], v[56:59], off
	s_waitcnt lgkmcnt(0)
	v_add_f32_e32 v48, v48, v49
	ds_bpermute_b32 v49, v117, v48
	s_and_saveexec_b64 s[14:15], s[46:47]
	s_cbranch_execz .LBB0_1577
	s_waitcnt lgkmcnt(0)
	v_add_f32_e32 v48, v48, v49
	v_mul_f32_e32 v48, 0x4f800000, v48
	v_rndne_f32_e32 v48, v48
	v_mul_f32_e32 v49, 0x2f800000, v48
	v_floor_f32_e32 v49, v49
	v_fmac_f32_e32 v48, 0xcf800000, v49
	v_cvt_u32_f32_e32 v48, v48
	v_cvt_u32_f32_e32 v49, v49
	v_mov_b32_e32 v240, v48
	v_mov_b32_e32 v241, v49
